# merge hook/epilogue: removed 482 redundant NaN-canonicalizing v_max x,x,x in front of the 1e-20 clamp (exact for finite gates), on top of the late stagger barrier
# baseline (speedup 1.0000x reference)
.LBB0_1008:
	s_andn2_b64 vcc, exec, s[28:29]
	s_cbranch_vccnz .LBB0_1003
	v_mov_b32_e32 v129, v192
	v_mov_b32_e32 v128, v193
	s_and_b32 s6, s26, 0xc00
	v_add_u32_e32 v198, s59, v129
	v_mov_b64_e32 v[188:189], s[10:11]
	v_lshl_add_u32 v128, v128, 3, s58
	s_addk_i32 s6, 0xfc00
	v_mad_i64_i32 v[130:131], s[28:29], v198, s49, v[188:189]
	v_ashrrev_i32_e32 v129, 31, v128
	s_lshl_b64 s[28:29], s[6:7], 1
	v_lshl_add_u64 v[130:131], v[130:131], 0, s[28:29]
	v_lshlrev_b64 v[190:191], 1, v[128:129]
	v_lshl_add_u64 v[128:129], v[130:131], 0, v[190:191]
	v_lshl_add_u64 v[130:131], v[128:129], 0, s[18:19]
	global_load_dwordx4 v[200:203], v[128:129], off offset:3584
	global_load_dwordx4 v[206:209], v[128:129], off offset:3840
	global_load_dwordx4 v[210:213], v[130:131], off offset:2048
	global_load_dwordx4 v[214:217], v[130:131], off offset:2304
	v_add_u32_e32 v128, 16, v198
	v_mad_i64_i32 v[128:129], s[30:31], v128, s49, v[188:189]
	v_lshl_add_u64 v[128:129], v[128:129], 0, s[28:29]
	v_lshl_add_u64 v[128:129], v[128:129], 0, v[190:191]
	v_lshl_add_u64 v[130:131], v[128:129], 0, s[18:19]
	global_load_dwordx4 v[218:221], v[128:129], off offset:3584
	global_load_dwordx4 v[160:163], v[128:129], off offset:3840
	global_load_dwordx4 v[222:225], v[130:131], off offset:2048
	global_load_dwordx4 v[164:167], v[130:131], off offset:2304
	v_add_u32_e32 v128, 32, v198
	v_mad_i64_i32 v[128:129], s[30:31], v128, s49, v[188:189]
	v_lshl_add_u64 v[128:129], v[128:129], 0, s[28:29]
	v_lshl_add_u64 v[128:129], v[128:129], 0, v[190:191]
	v_lshl_add_u64 v[130:131], v[128:129], 0, s[18:19]
	global_load_dwordx4 v[152:155], v[128:129], off offset:3584
	global_load_dwordx4 v[144:147], v[128:129], off offset:3840
	global_load_dwordx4 v[156:159], v[130:131], off offset:2048
	global_load_dwordx4 v[148:151], v[130:131], off offset:2304
	v_add_u32_e32 v128, 48, v198
	v_mad_i64_i32 v[128:129], s[30:31], v128, s49, v[188:189]
	v_lshl_add_u64 v[128:129], v[128:129], 0, s[28:29]
	v_lshl_add_u64 v[128:129], v[128:129], 0, v[190:191]
	v_lshl_add_u64 v[132:133], v[128:129], 0, s[18:19]
	global_load_dwordx4 v[136:139], v[128:129], off offset:3584
	s_nop 0
	global_load_dwordx4 v[128:131], v[128:129], off offset:3840
	s_nop 0
	global_load_dwordx4 v[140:143], v[132:133], off offset:2048
	s_nop 0
	global_load_dwordx4 v[132:135], v[132:133], off offset:2304
	s_waitcnt vmcnt(0)
	v_lshlrev_b32_e32 v199, 16, v210
	v_max_f32_e32 v199, 0x1e3ce508, v199
	v_rcp_f32_e32 v226, v199
	v_and_b32_e32 v199, 0xffff0000, v210
	v_max_f32_e32 v199, 0x1e3ce508, v199
	v_rcp_f32_e32 v227, v199
	v_lshlrev_b32_e32 v199, 16, v211
	v_max_f32_e32 v199, 0x1e3ce508, v199
	v_rcp_f32_e32 v210, v199
	v_and_b32_e32 v199, 0xffff0000, v211
	v_max_f32_e32 v199, 0x1e3ce508, v199
	v_rcp_f32_e32 v211, v199
	v_lshlrev_b32_e32 v199, 16, v212
	v_lshlrev_b32_e32 v228, 16, v200
	v_and_b32_e32 v229, 0xffff0000, v200
	v_lshlrev_b32_e32 v200, 16, v201
	v_and_b32_e32 v201, 0xffff0000, v201
	v_max_f32_e32 v199, 0x1e3ce508, v199
	v_pk_mul_f32 v[200:201], v[210:211], v[200:201]
	v_rcp_f32_e32 v210, v199
	v_and_b32_e32 v199, 0xffff0000, v212
	v_max_f32_e32 v199, 0x1e3ce508, v199
	v_rcp_f32_e32 v211, v199
	v_lshlrev_b32_e32 v199, 16, v213
	v_pk_mul_f32 v[126:127], v[126:127], v[200:201]
	v_lshlrev_b32_e32 v200, 16, v202
	v_and_b32_e32 v201, 0xffff0000, v202
	v_max_f32_e32 v199, 0x1e3ce508, v199
	v_pk_mul_f32 v[200:201], v[210:211], v[200:201]
	v_rcp_f32_e32 v210, v199
	v_and_b32_e32 v199, 0xffff0000, v213
	v_max_f32_e32 v199, 0x1e3ce508, v199
	v_rcp_f32_e32 v211, v199
	v_lshlrev_b32_e32 v199, 16, v214
	v_max_f32_e32 v199, 0x1e3ce508, v199
	v_rcp_f32_e32 v202, v199
	v_and_b32_e32 v199, 0xffff0000, v214
	v_max_f32_e32 v199, 0x1e3ce508, v199
	v_pk_mul_f32 v[120:121], v[120:121], v[200:201]
	v_lshlrev_b32_e32 v200, 16, v203
	v_and_b32_e32 v201, 0xffff0000, v203
	v_rcp_f32_e32 v203, v199
	v_lshlrev_b32_e32 v199, 16, v215
	v_pk_mul_f32 v[200:201], v[210:211], v[200:201]
	v_pk_mul_f32 v[122:123], v[122:123], v[200:201]
	v_lshlrev_b32_e32 v200, 16, v206
	v_and_b32_e32 v201, 0xffff0000, v206
	v_max_f32_e32 v199, 0x1e3ce508, v199
	v_pk_mul_f32 v[200:201], v[202:203], v[200:201]
	v_rcp_f32_e32 v202, v199
	v_and_b32_e32 v199, 0xffff0000, v215
	v_max_f32_e32 v199, 0x1e3ce508, v199
	v_rcp_f32_e32 v203, v199
	v_lshlrev_b32_e32 v199, 16, v216
	v_pk_mul_f32 v[116:117], v[116:117], v[200:201]
	v_lshlrev_b32_e32 v200, 16, v207
	v_and_b32_e32 v201, 0xffff0000, v207
	v_max_f32_e32 v199, 0x1e3ce508, v199
	v_pk_mul_f32 v[200:201], v[202:203], v[200:201]
	v_rcp_f32_e32 v202, v199
	v_and_b32_e32 v199, 0xffff0000, v216
	v_max_f32_e32 v199, 0x1e3ce508, v199
	v_rcp_f32_e32 v203, v199
	v_lshlrev_b32_e32 v199, 16, v217
	v_pk_mul_f32 v[118:119], v[118:119], v[200:201]
	v_lshlrev_b32_e32 v200, 16, v208
	v_and_b32_e32 v201, 0xffff0000, v208
	v_max_f32_e32 v199, 0x1e3ce508, v199
	v_pk_mul_f32 v[200:201], v[202:203], v[200:201]
	v_rcp_f32_e32 v202, v199
	v_and_b32_e32 v199, 0xffff0000, v217
	v_max_f32_e32 v199, 0x1e3ce508, v199
	v_rcp_f32_e32 v203, v199
	v_lshlrev_b32_e32 v199, 16, v222
	v_pk_mul_f32 v[112:113], v[112:113], v[200:201]
	v_lshlrev_b32_e32 v200, 16, v209
	v_and_b32_e32 v201, 0xffff0000, v209
	v_max_f32_e32 v199, 0x1e3ce508, v199
	v_pk_mul_f32 v[200:201], v[202:203], v[200:201]
	v_rcp_f32_e32 v202, v199
	v_and_b32_e32 v199, 0xffff0000, v222
	v_max_f32_e32 v199, 0x1e3ce508, v199
	v_rcp_f32_e32 v203, v199
	v_lshlrev_b32_e32 v199, 16, v223
	v_pk_mul_f32 v[114:115], v[114:115], v[200:201]
	v_lshlrev_b32_e32 v200, 16, v218
	v_and_b32_e32 v201, 0xffff0000, v218
	v_max_f32_e32 v199, 0x1e3ce508, v199
	v_pk_mul_f32 v[200:201], v[202:203], v[200:201]
	v_rcp_f32_e32 v202, v199
	v_and_b32_e32 v199, 0xffff0000, v223
	v_max_f32_e32 v199, 0x1e3ce508, v199
	v_rcp_f32_e32 v203, v199
	v_lshlrev_b32_e32 v199, 16, v224
	v_pk_mul_f32 v[108:109], v[108:109], v[200:201]
	v_lshlrev_b32_e32 v200, 16, v219
	v_and_b32_e32 v201, 0xffff0000, v219
	v_max_f32_e32 v199, 0x1e3ce508, v199
	v_pk_mul_f32 v[200:201], v[202:203], v[200:201]
	v_rcp_f32_e32 v202, v199
	v_and_b32_e32 v199, 0xffff0000, v224
	v_max_f32_e32 v199, 0x1e3ce508, v199
	v_rcp_f32_e32 v203, v199
	v_lshlrev_b32_e32 v199, 16, v225
	v_pk_mul_f32 v[110:111], v[110:111], v[200:201]
	v_lshlrev_b32_e32 v200, 16, v220
	v_and_b32_e32 v201, 0xffff0000, v220
	v_max_f32_e32 v199, 0x1e3ce508, v199
	v_pk_mul_f32 v[200:201], v[202:203], v[200:201]
	v_rcp_f32_e32 v202, v199
	v_and_b32_e32 v199, 0xffff0000, v225
	v_max_f32_e32 v199, 0x1e3ce508, v199
	v_rcp_f32_e32 v203, v199
	v_pk_mul_f32 v[104:105], v[104:105], v[200:201]
	v_lshlrev_b32_e32 v200, 16, v221
	v_and_b32_e32 v201, 0xffff0000, v221
	v_pk_mul_f32 v[200:201], v[202:203], v[200:201]
	v_lshlrev_b32_e32 v199, 16, v164
	v_and_b32_e32 v164, 0xffff0000, v164
	v_pk_mul_f32 v[106:107], v[106:107], v[200:201]
	v_lshlrev_b32_e32 v200, 16, v160
	v_and_b32_e32 v201, 0xffff0000, v160
	v_lshlrev_b32_e32 v160, 16, v165
	v_max_f32_e32 v164, 0x1e3ce508, v164
	v_max_f32_e32 v160, 0x1e3ce508, v160
	v_rcp_f32_e32 v203, v164
	v_rcp_f32_e32 v164, v160
	v_and_b32_e32 v160, 0xffff0000, v165
	v_max_f32_e32 v160, 0x1e3ce508, v160
	v_rcp_f32_e32 v165, v160
	v_lshlrev_b32_e32 v160, 16, v161
	v_and_b32_e32 v161, 0xffff0000, v161
	v_max_f32_e32 v199, v199, v199
	v_pk_mul_f32 v[160:161], v[164:165], v[160:161]
	v_lshlrev_b32_e32 v164, 16, v166
	v_and_b32_e32 v165, 0xffff0000, v166
	v_max_f32_e32 v164, 0x1e3ce508, v164
	v_max_f32_e32 v165, 0x1e3ce508, v165
	v_rcp_f32_e32 v164, v164
	v_rcp_f32_e32 v165, v165
	v_pk_mul_f32 v[102:103], v[102:103], v[160:161]
	v_lshlrev_b32_e32 v160, 16, v162
	v_and_b32_e32 v161, 0xffff0000, v162
	v_lshlrev_b32_e32 v162, 16, v167
	v_max_f32_e32 v162, 0x1e3ce508, v162
	v_pk_mul_f32 v[160:161], v[164:165], v[160:161]
	v_rcp_f32_e32 v164, v162
	v_and_b32_e32 v162, 0xffff0000, v167
	v_max_f32_e32 v162, 0x1e3ce508, v162
	v_rcp_f32_e32 v165, v162
	v_pk_mul_f32 v[96:97], v[96:97], v[160:161]
	v_lshlrev_b32_e32 v160, 16, v163
	v_and_b32_e32 v161, 0xffff0000, v163
	v_pk_mul_f32 v[160:161], v[164:165], v[160:161]
	v_lshlrev_b32_e32 v162, 16, v156
	v_and_b32_e32 v156, 0xffff0000, v156
	v_pk_mul_f32 v[98:99], v[98:99], v[160:161]
	v_lshlrev_b32_e32 v160, 16, v152
	v_and_b32_e32 v161, 0xffff0000, v152
	v_lshlrev_b32_e32 v152, 16, v157
	v_max_f32_e32 v156, 0x1e3ce508, v156
	v_max_f32_e32 v152, 0x1e3ce508, v152
	v_rcp_f32_e32 v163, v156
	v_rcp_f32_e32 v156, v152
	v_and_b32_e32 v152, 0xffff0000, v157
	v_max_f32_e32 v152, 0x1e3ce508, v152
	v_rcp_f32_e32 v157, v152
	v_lshlrev_b32_e32 v152, 16, v153
	v_and_b32_e32 v153, 0xffff0000, v153
	v_max_f32_e32 v162, v162, v162
	v_pk_mul_f32 v[152:153], v[156:157], v[152:153]
	v_lshlrev_b32_e32 v156, 16, v158
	v_and_b32_e32 v157, 0xffff0000, v158
	v_max_f32_e32 v156, 0x1e3ce508, v156
	v_max_f32_e32 v157, 0x1e3ce508, v157
	v_rcp_f32_e32 v156, v156
	v_rcp_f32_e32 v157, v157
	v_pk_mul_f32 v[94:95], v[94:95], v[152:153]
	v_lshlrev_b32_e32 v152, 16, v154
	v_and_b32_e32 v153, 0xffff0000, v154
	v_lshlrev_b32_e32 v154, 16, v159
	v_max_f32_e32 v154, 0x1e3ce508, v154
	v_pk_mul_f32 v[152:153], v[156:157], v[152:153]
	v_rcp_f32_e32 v156, v154
	v_and_b32_e32 v154, 0xffff0000, v159
	v_max_f32_e32 v154, 0x1e3ce508, v154
	v_rcp_f32_e32 v157, v154
	v_pk_mul_f32 v[88:89], v[88:89], v[152:153]
	v_lshlrev_b32_e32 v152, 16, v155
	v_and_b32_e32 v153, 0xffff0000, v155
	v_pk_mul_f32 v[152:153], v[156:157], v[152:153]
	v_lshlrev_b32_e32 v154, 16, v148
	v_and_b32_e32 v148, 0xffff0000, v148
	v_pk_mul_f32 v[90:91], v[90:91], v[152:153]
	v_lshlrev_b32_e32 v152, 16, v144
	v_and_b32_e32 v153, 0xffff0000, v144
	v_lshlrev_b32_e32 v144, 16, v149
	v_max_f32_e32 v148, 0x1e3ce508, v148
	v_max_f32_e32 v144, 0x1e3ce508, v144
	v_rcp_f32_e32 v155, v148
	v_rcp_f32_e32 v148, v144
	v_and_b32_e32 v144, 0xffff0000, v149
	v_max_f32_e32 v144, 0x1e3ce508, v144
	v_rcp_f32_e32 v149, v144
	v_lshlrev_b32_e32 v144, 16, v145
	v_and_b32_e32 v145, 0xffff0000, v145
	v_max_f32_e32 v154, v154, v154
	v_pk_mul_f32 v[144:145], v[148:149], v[144:145]
	v_lshlrev_b32_e32 v148, 16, v150
	v_and_b32_e32 v149, 0xffff0000, v150
	v_max_f32_e32 v148, 0x1e3ce508, v148
	v_max_f32_e32 v149, 0x1e3ce508, v149
	v_rcp_f32_e32 v148, v148
	v_rcp_f32_e32 v149, v149
	v_pk_mul_f32 v[86:87], v[86:87], v[144:145]
	v_lshlrev_b32_e32 v144, 16, v146
	v_and_b32_e32 v145, 0xffff0000, v146
	v_lshlrev_b32_e32 v146, 16, v151
	v_max_f32_e32 v146, 0x1e3ce508, v146
	v_pk_mul_f32 v[144:145], v[148:149], v[144:145]
	v_rcp_f32_e32 v148, v146
	v_and_b32_e32 v146, 0xffff0000, v151
	v_max_f32_e32 v146, 0x1e3ce508, v146
	v_rcp_f32_e32 v149, v146
	v_pk_mul_f32 v[80:81], v[80:81], v[144:145]
	v_lshlrev_b32_e32 v144, 16, v147
	v_and_b32_e32 v145, 0xffff0000, v147
	v_pk_mul_f32 v[144:145], v[148:149], v[144:145]
	v_lshlrev_b32_e32 v146, 16, v140
	v_and_b32_e32 v140, 0xffff0000, v140
	v_pk_mul_f32 v[82:83], v[82:83], v[144:145]
	v_lshlrev_b32_e32 v144, 16, v136
	v_and_b32_e32 v145, 0xffff0000, v136
	v_lshlrev_b32_e32 v136, 16, v141
	v_max_f32_e32 v140, 0x1e3ce508, v140
	v_max_f32_e32 v136, 0x1e3ce508, v136
	v_rcp_f32_e32 v147, v140
	v_rcp_f32_e32 v140, v136
	v_and_b32_e32 v136, 0xffff0000, v141
	v_max_f32_e32 v136, 0x1e3ce508, v136
	v_rcp_f32_e32 v141, v136
	v_lshlrev_b32_e32 v136, 16, v137
	v_and_b32_e32 v137, 0xffff0000, v137
	v_max_f32_e32 v146, v146, v146
	v_pk_mul_f32 v[136:137], v[140:141], v[136:137]
	v_lshlrev_b32_e32 v140, 16, v142
	v_and_b32_e32 v141, 0xffff0000, v142
	v_max_f32_e32 v140, 0x1e3ce508, v140
	v_max_f32_e32 v141, 0x1e3ce508, v141
	v_rcp_f32_e32 v140, v140
	v_rcp_f32_e32 v141, v141
	v_pk_mul_f32 v[78:79], v[78:79], v[136:137]
	v_lshlrev_b32_e32 v136, 16, v138
	v_and_b32_e32 v137, 0xffff0000, v138
	v_lshlrev_b32_e32 v138, 16, v143
	v_max_f32_e32 v138, 0x1e3ce508, v138
	v_pk_mul_f32 v[136:137], v[140:141], v[136:137]
	v_rcp_f32_e32 v140, v138
	v_and_b32_e32 v138, 0xffff0000, v143
	v_max_f32_e32 v138, 0x1e3ce508, v138
	v_rcp_f32_e32 v141, v138
	v_pk_mul_f32 v[72:73], v[72:73], v[136:137]
	v_lshlrev_b32_e32 v136, 16, v139
	v_and_b32_e32 v137, 0xffff0000, v139
	v_pk_mul_f32 v[136:137], v[140:141], v[136:137]
	v_lshlrev_b32_e32 v138, 16, v132
	v_and_b32_e32 v132, 0xffff0000, v132
	v_pk_mul_f32 v[74:75], v[74:75], v[136:137]
	v_lshlrev_b32_e32 v136, 16, v128
	v_and_b32_e32 v137, 0xffff0000, v128
	v_lshlrev_b32_e32 v128, 16, v133
	v_max_f32_e32 v132, 0x1e3ce508, v132
	v_max_f32_e32 v128, 0x1e3ce508, v128
	v_rcp_f32_e32 v139, v132
	v_rcp_f32_e32 v132, v128
	v_and_b32_e32 v128, 0xffff0000, v133
	v_max_f32_e32 v128, 0x1e3ce508, v128
	v_rcp_f32_e32 v133, v128
	v_lshlrev_b32_e32 v128, 16, v129
	v_and_b32_e32 v129, 0xffff0000, v129
	v_pk_mul_f32 v[128:129], v[132:133], v[128:129]
	v_lshlrev_b32_e32 v132, 16, v134
	v_and_b32_e32 v133, 0xffff0000, v134
	v_max_f32_e32 v132, 0x1e3ce508, v132
	v_max_f32_e32 v133, 0x1e3ce508, v133
	v_rcp_f32_e32 v132, v132
	v_rcp_f32_e32 v133, v133
	v_pk_mul_f32 v[70:71], v[70:71], v[128:129]
	v_lshlrev_b32_e32 v128, 16, v130
	v_and_b32_e32 v129, 0xffff0000, v130
	v_lshlrev_b32_e32 v130, 16, v135
	v_max_f32_e32 v130, 0x1e3ce508, v130
	v_pk_mul_f32 v[128:129], v[132:133], v[128:129]
	v_rcp_f32_e32 v132, v130
	v_and_b32_e32 v130, 0xffff0000, v135
	v_max_f32_e32 v199, 0x1e3ce508, v199
	v_max_f32_e32 v162, 0x1e3ce508, v162
	v_max_f32_e32 v154, 0x1e3ce508, v154
	v_max_f32_e32 v146, 0x1e3ce508, v146
	v_max_f32_e32 v138, 0x1e3ce508, v138
	v_max_f32_e32 v130, 0x1e3ce508, v130
	v_rcp_f32_e32 v202, v199
	v_rcp_f32_e32 v162, v162
	v_rcp_f32_e32 v154, v154
	v_rcp_f32_e32 v146, v146
	v_rcp_f32_e32 v138, v138
	v_rcp_f32_e32 v133, v130
	v_pk_mul_f32 v[64:65], v[64:65], v[128:129]
	v_lshlrev_b32_e32 v128, 16, v131
	v_and_b32_e32 v129, 0xffff0000, v131
	v_pk_mul_f32 v[226:227], v[226:227], v[228:229]
	v_pk_mul_f32 v[200:201], v[202:203], v[200:201]
	v_pk_mul_f32 v[160:161], v[162:163], v[160:161]
	v_pk_mul_f32 v[152:153], v[154:155], v[152:153]
	v_pk_mul_f32 v[144:145], v[146:147], v[144:145]
	v_pk_mul_f32 v[136:137], v[138:139], v[136:137]
	v_pk_mul_f32 v[128:129], v[132:133], v[128:129]
	v_pk_mul_f32 v[124:125], v[124:125], v[226:227]
	v_pk_mul_f32 v[100:101], v[100:101], v[200:201]
	v_pk_mul_f32 v[92:93], v[92:93], v[160:161]
	v_pk_mul_f32 v[84:85], v[84:85], v[152:153]
	v_pk_mul_f32 v[76:77], v[76:77], v[144:145]
	v_pk_mul_f32 v[68:69], v[68:69], v[136:137]
	v_pk_mul_f32 v[66:67], v[66:67], v[128:129]
	v_add_u32_e32 v128, 0x80, v198
	v_mad_i64_i32 v[128:129], s[30:31], v128, s49, v[188:189]
	v_lshl_add_u64 v[128:129], v[128:129], 0, s[28:29]
	v_lshl_add_u64 v[128:129], v[128:129], 0, v[190:191]
	v_lshl_add_u64 v[130:131], v[128:129], 0, s[18:19]
	global_load_dwordx4 v[200:203], v[128:129], off offset:3584
	global_load_dwordx4 v[206:209], v[128:129], off offset:3840
	global_load_dwordx4 v[210:213], v[130:131], off offset:2048
	global_load_dwordx4 v[214:217], v[130:131], off offset:2304
	v_add_u32_e32 v128, 0x90, v198
	v_mad_i64_i32 v[128:129], s[30:31], v128, s49, v[188:189]
	v_lshl_add_u64 v[128:129], v[128:129], 0, s[28:29]
	v_lshl_add_u64 v[128:129], v[128:129], 0, v[190:191]
	v_lshl_add_u64 v[130:131], v[128:129], 0, s[18:19]
	global_load_dwordx4 v[218:221], v[128:129], off offset:3584
	global_load_dwordx4 v[160:163], v[128:129], off offset:3840
	global_load_dwordx4 v[222:225], v[130:131], off offset:2048
	global_load_dwordx4 v[164:167], v[130:131], off offset:2304
	v_add_u32_e32 v128, 0xa0, v198
	v_mad_i64_i32 v[128:129], s[30:31], v128, s49, v[188:189]
	v_lshl_add_u64 v[128:129], v[128:129], 0, s[28:29]
	v_lshl_add_u64 v[128:129], v[128:129], 0, v[190:191]
	v_lshl_add_u64 v[130:131], v[128:129], 0, s[18:19]
	global_load_dwordx4 v[152:155], v[128:129], off offset:3584
	global_load_dwordx4 v[144:147], v[128:129], off offset:3840
	global_load_dwordx4 v[156:159], v[130:131], off offset:2048
	global_load_dwordx4 v[148:151], v[130:131], off offset:2304
	v_add_u32_e32 v128, 0xb0, v198
	v_mad_i64_i32 v[128:129], s[30:31], v128, s49, v[188:189]
	v_lshl_add_u64 v[128:129], v[128:129], 0, s[28:29]
	v_lshl_add_u64 v[128:129], v[128:129], 0, v[190:191]
	v_lshl_add_u64 v[132:133], v[128:129], 0, s[18:19]
	global_load_dwordx4 v[136:139], v[128:129], off offset:3584
	s_nop 0
	global_load_dwordx4 v[128:131], v[128:129], off offset:3840
	s_nop 0
	global_load_dwordx4 v[140:143], v[132:133], off offset:2048
	s_nop 0
	global_load_dwordx4 v[132:135], v[132:133], off offset:2304
	s_waitcnt vmcnt(13)
	v_lshlrev_b32_e32 v188, 16, v210
	v_and_b32_e32 v189, 0xffff0000, v210
	v_max_f32_e32 v188, 0x1e3ce508, v188
	v_max_f32_e32 v189, 0x1e3ce508, v189
	v_rcp_f32_e32 v188, v188
	v_rcp_f32_e32 v189, v189
	v_lshlrev_b32_e32 v190, 16, v200
	v_and_b32_e32 v191, 0xffff0000, v200
	v_pk_mul_f32 v[188:189], v[188:189], v[190:191]
	v_lshlrev_b32_e32 v190, 16, v211
	v_and_b32_e32 v191, 0xffff0000, v211
	v_max_f32_e32 v190, 0x1e3ce508, v190
	v_max_f32_e32 v191, 0x1e3ce508, v191
	v_rcp_f32_e32 v190, v190
	v_rcp_f32_e32 v191, v191
	v_pk_mul_f32 v[60:61], v[60:61], v[188:189]
	v_lshlrev_b32_e32 v188, 16, v201
	v_and_b32_e32 v189, 0xffff0000, v201
	v_pk_mul_f32 v[188:189], v[190:191], v[188:189]
	v_lshlrev_b32_e32 v190, 16, v212
	v_and_b32_e32 v191, 0xffff0000, v212
	v_max_f32_e32 v190, 0x1e3ce508, v190
	v_max_f32_e32 v191, 0x1e3ce508, v191
	v_rcp_f32_e32 v190, v190
	v_rcp_f32_e32 v191, v191
	v_pk_mul_f32 v[62:63], v[62:63], v[188:189]
	v_lshlrev_b32_e32 v188, 16, v202
	v_and_b32_e32 v189, 0xffff0000, v202
	v_pk_mul_f32 v[188:189], v[190:191], v[188:189]
	v_lshlrev_b32_e32 v190, 16, v213
	v_and_b32_e32 v191, 0xffff0000, v213
	v_max_f32_e32 v190, 0x1e3ce508, v190
	v_max_f32_e32 v191, 0x1e3ce508, v191
	v_rcp_f32_e32 v190, v190
	v_rcp_f32_e32 v191, v191
	v_pk_mul_f32 v[56:57], v[56:57], v[188:189]
	v_lshlrev_b32_e32 v188, 16, v203
	v_and_b32_e32 v189, 0xffff0000, v203
	v_pk_mul_f32 v[188:189], v[190:191], v[188:189]
	s_waitcnt vmcnt(12)
	v_lshlrev_b32_e32 v190, 16, v214
	v_and_b32_e32 v191, 0xffff0000, v214
	v_max_f32_e32 v190, 0x1e3ce508, v190
	v_max_f32_e32 v191, 0x1e3ce508, v191
	v_rcp_f32_e32 v190, v190
	v_rcp_f32_e32 v191, v191
	v_pk_mul_f32 v[58:59], v[58:59], v[188:189]
	v_lshlrev_b32_e32 v188, 16, v206
	v_and_b32_e32 v189, 0xffff0000, v206
	v_pk_mul_f32 v[188:189], v[190:191], v[188:189]
	v_lshlrev_b32_e32 v190, 16, v215
	v_and_b32_e32 v191, 0xffff0000, v215
	v_max_f32_e32 v190, 0x1e3ce508, v190
	v_max_f32_e32 v191, 0x1e3ce508, v191
	v_rcp_f32_e32 v190, v190
	v_rcp_f32_e32 v191, v191
	v_pk_mul_f32 v[52:53], v[52:53], v[188:189]
	v_lshlrev_b32_e32 v188, 16, v207
	v_and_b32_e32 v189, 0xffff0000, v207
	v_pk_mul_f32 v[188:189], v[190:191], v[188:189]
	v_lshlrev_b32_e32 v190, 16, v216
	v_and_b32_e32 v191, 0xffff0000, v216
	v_max_f32_e32 v190, 0x1e3ce508, v190
	v_max_f32_e32 v191, 0x1e3ce508, v191
	v_rcp_f32_e32 v190, v190
	v_rcp_f32_e32 v191, v191
	v_pk_mul_f32 v[54:55], v[54:55], v[188:189]
	v_lshlrev_b32_e32 v188, 16, v208
	v_and_b32_e32 v189, 0xffff0000, v208
	v_pk_mul_f32 v[188:189], v[190:191], v[188:189]
	v_lshlrev_b32_e32 v190, 16, v217
	v_and_b32_e32 v191, 0xffff0000, v217
	v_max_f32_e32 v190, 0x1e3ce508, v190
	v_max_f32_e32 v191, 0x1e3ce508, v191
	v_rcp_f32_e32 v190, v190
	v_rcp_f32_e32 v191, v191
	v_pk_mul_f32 v[48:49], v[48:49], v[188:189]
	v_lshlrev_b32_e32 v188, 16, v209
	v_and_b32_e32 v189, 0xffff0000, v209
	v_pk_mul_f32 v[188:189], v[190:191], v[188:189]
	s_waitcnt vmcnt(9)
	v_lshlrev_b32_e32 v190, 16, v222
	v_and_b32_e32 v191, 0xffff0000, v222
	v_max_f32_e32 v190, 0x1e3ce508, v190
	v_max_f32_e32 v191, 0x1e3ce508, v191
	v_rcp_f32_e32 v190, v190
	v_rcp_f32_e32 v191, v191
	v_pk_mul_f32 v[50:51], v[50:51], v[188:189]
	v_lshlrev_b32_e32 v188, 16, v218
	v_and_b32_e32 v189, 0xffff0000, v218
	v_pk_mul_f32 v[188:189], v[190:191], v[188:189]
	v_lshlrev_b32_e32 v190, 16, v223
	v_and_b32_e32 v191, 0xffff0000, v223
	v_max_f32_e32 v190, 0x1e3ce508, v190
	v_max_f32_e32 v191, 0x1e3ce508, v191
	v_rcp_f32_e32 v190, v190
	v_rcp_f32_e32 v191, v191
	v_pk_mul_f32 v[44:45], v[44:45], v[188:189]
	v_lshlrev_b32_e32 v188, 16, v219
	v_and_b32_e32 v189, 0xffff0000, v219
	v_pk_mul_f32 v[188:189], v[190:191], v[188:189]
	v_lshlrev_b32_e32 v190, 16, v224
	v_and_b32_e32 v191, 0xffff0000, v224
	v_max_f32_e32 v190, 0x1e3ce508, v190
	v_max_f32_e32 v191, 0x1e3ce508, v191
	v_rcp_f32_e32 v190, v190
	v_rcp_f32_e32 v191, v191
	v_pk_mul_f32 v[46:47], v[46:47], v[188:189]
	v_lshlrev_b32_e32 v188, 16, v220
	v_and_b32_e32 v189, 0xffff0000, v220
	v_pk_mul_f32 v[188:189], v[190:191], v[188:189]
	v_lshlrev_b32_e32 v190, 16, v225
	v_and_b32_e32 v191, 0xffff0000, v225
	v_max_f32_e32 v190, 0x1e3ce508, v190
	v_max_f32_e32 v191, 0x1e3ce508, v191
	v_rcp_f32_e32 v190, v190
	v_rcp_f32_e32 v191, v191
	v_pk_mul_f32 v[40:41], v[40:41], v[188:189]
	v_lshlrev_b32_e32 v188, 16, v221
	v_and_b32_e32 v189, 0xffff0000, v221
	v_pk_mul_f32 v[188:189], v[190:191], v[188:189]
	s_waitcnt vmcnt(8)
	v_lshlrev_b32_e32 v190, 16, v164
	v_and_b32_e32 v164, 0xffff0000, v164
	v_pk_mul_f32 v[42:43], v[42:43], v[188:189]
	v_lshlrev_b32_e32 v188, 16, v160
	v_and_b32_e32 v189, 0xffff0000, v160
	v_lshlrev_b32_e32 v160, 16, v165
	v_max_f32_e32 v164, 0x1e3ce508, v164
	v_max_f32_e32 v160, 0x1e3ce508, v160
	v_rcp_f32_e32 v191, v164
	v_rcp_f32_e32 v164, v160
	v_and_b32_e32 v160, 0xffff0000, v165
	v_max_f32_e32 v160, 0x1e3ce508, v160
	v_rcp_f32_e32 v165, v160
	v_lshlrev_b32_e32 v160, 16, v161
	v_and_b32_e32 v161, 0xffff0000, v161
	v_max_f32_e32 v190, v190, v190
	v_pk_mul_f32 v[160:161], v[164:165], v[160:161]
	v_lshlrev_b32_e32 v164, 16, v166
	v_and_b32_e32 v165, 0xffff0000, v166
	v_max_f32_e32 v164, 0x1e3ce508, v164
	v_max_f32_e32 v165, 0x1e3ce508, v165
	v_rcp_f32_e32 v164, v164
	v_rcp_f32_e32 v165, v165
	v_pk_mul_f32 v[38:39], v[38:39], v[160:161]
	v_lshlrev_b32_e32 v160, 16, v162
	v_and_b32_e32 v161, 0xffff0000, v162
	v_lshlrev_b32_e32 v162, 16, v167
	v_max_f32_e32 v162, 0x1e3ce508, v162
	v_pk_mul_f32 v[160:161], v[164:165], v[160:161]
	v_rcp_f32_e32 v164, v162
	v_and_b32_e32 v162, 0xffff0000, v167
	v_max_f32_e32 v162, 0x1e3ce508, v162
	v_rcp_f32_e32 v165, v162
	v_pk_mul_f32 v[32:33], v[32:33], v[160:161]
	v_lshlrev_b32_e32 v160, 16, v163
	v_and_b32_e32 v161, 0xffff0000, v163
	v_pk_mul_f32 v[160:161], v[164:165], v[160:161]
	s_waitcnt vmcnt(5)
	v_lshlrev_b32_e32 v162, 16, v156
	v_and_b32_e32 v156, 0xffff0000, v156
	v_pk_mul_f32 v[34:35], v[34:35], v[160:161]
	v_lshlrev_b32_e32 v160, 16, v152
	v_and_b32_e32 v161, 0xffff0000, v152
	v_lshlrev_b32_e32 v152, 16, v157
	v_max_f32_e32 v156, 0x1e3ce508, v156
	v_max_f32_e32 v152, 0x1e3ce508, v152
	v_rcp_f32_e32 v163, v156
	v_rcp_f32_e32 v156, v152
	v_and_b32_e32 v152, 0xffff0000, v157
	v_max_f32_e32 v152, 0x1e3ce508, v152
	v_rcp_f32_e32 v157, v152
	v_lshlrev_b32_e32 v152, 16, v153
	v_and_b32_e32 v153, 0xffff0000, v153
	v_max_f32_e32 v162, v162, v162
	v_pk_mul_f32 v[152:153], v[156:157], v[152:153]
	v_lshlrev_b32_e32 v156, 16, v158
	v_and_b32_e32 v157, 0xffff0000, v158
	v_max_f32_e32 v156, 0x1e3ce508, v156
	v_max_f32_e32 v157, 0x1e3ce508, v157
	v_rcp_f32_e32 v156, v156
	v_rcp_f32_e32 v157, v157
	v_pk_mul_f32 v[30:31], v[30:31], v[152:153]
	v_lshlrev_b32_e32 v152, 16, v154
	v_and_b32_e32 v153, 0xffff0000, v154
	v_lshlrev_b32_e32 v154, 16, v159
	v_max_f32_e32 v154, 0x1e3ce508, v154
	v_pk_mul_f32 v[152:153], v[156:157], v[152:153]
	v_rcp_f32_e32 v156, v154
	v_and_b32_e32 v154, 0xffff0000, v159
	v_max_f32_e32 v154, 0x1e3ce508, v154
	v_rcp_f32_e32 v157, v154
	v_pk_mul_f32 v[24:25], v[24:25], v[152:153]
	v_lshlrev_b32_e32 v152, 16, v155
	v_and_b32_e32 v153, 0xffff0000, v155
	v_pk_mul_f32 v[152:153], v[156:157], v[152:153]
	s_waitcnt vmcnt(4)
	v_lshlrev_b32_e32 v154, 16, v148
	v_and_b32_e32 v148, 0xffff0000, v148
	v_pk_mul_f32 v[26:27], v[26:27], v[152:153]
	v_lshlrev_b32_e32 v152, 16, v144
	v_and_b32_e32 v153, 0xffff0000, v144
	v_lshlrev_b32_e32 v144, 16, v149
	v_max_f32_e32 v148, 0x1e3ce508, v148
	v_max_f32_e32 v144, 0x1e3ce508, v144
	v_rcp_f32_e32 v155, v148
	v_rcp_f32_e32 v148, v144
	v_and_b32_e32 v144, 0xffff0000, v149
	v_max_f32_e32 v144, 0x1e3ce508, v144
	v_rcp_f32_e32 v149, v144
	v_lshlrev_b32_e32 v144, 16, v145
	v_and_b32_e32 v145, 0xffff0000, v145
	v_max_f32_e32 v154, v154, v154
	v_pk_mul_f32 v[144:145], v[148:149], v[144:145]
	v_lshlrev_b32_e32 v148, 16, v150
	v_and_b32_e32 v149, 0xffff0000, v150
	v_max_f32_e32 v148, 0x1e3ce508, v148
	v_max_f32_e32 v149, 0x1e3ce508, v149
	v_rcp_f32_e32 v148, v148
	v_rcp_f32_e32 v149, v149
	v_pk_mul_f32 v[22:23], v[22:23], v[144:145]
	v_lshlrev_b32_e32 v144, 16, v146
	v_and_b32_e32 v145, 0xffff0000, v146
	v_lshlrev_b32_e32 v146, 16, v151
	v_max_f32_e32 v146, 0x1e3ce508, v146
	v_pk_mul_f32 v[144:145], v[148:149], v[144:145]
	v_rcp_f32_e32 v148, v146
	v_and_b32_e32 v146, 0xffff0000, v151
	v_max_f32_e32 v146, 0x1e3ce508, v146
	v_rcp_f32_e32 v149, v146
	v_pk_mul_f32 v[16:17], v[16:17], v[144:145]
	v_lshlrev_b32_e32 v144, 16, v147
	v_and_b32_e32 v145, 0xffff0000, v147
	v_pk_mul_f32 v[144:145], v[148:149], v[144:145]
	s_waitcnt vmcnt(1)
	v_lshlrev_b32_e32 v146, 16, v140
	v_and_b32_e32 v140, 0xffff0000, v140
	v_pk_mul_f32 v[18:19], v[18:19], v[144:145]
	v_lshlrev_b32_e32 v144, 16, v136
	v_and_b32_e32 v145, 0xffff0000, v136
	v_lshlrev_b32_e32 v136, 16, v141
	v_max_f32_e32 v140, 0x1e3ce508, v140
	v_max_f32_e32 v136, 0x1e3ce508, v136
	v_rcp_f32_e32 v147, v140
	v_rcp_f32_e32 v140, v136
	v_and_b32_e32 v136, 0xffff0000, v141
	v_max_f32_e32 v136, 0x1e3ce508, v136
	v_rcp_f32_e32 v141, v136
	v_lshlrev_b32_e32 v136, 16, v137
	v_and_b32_e32 v137, 0xffff0000, v137
	v_max_f32_e32 v146, v146, v146
	v_pk_mul_f32 v[136:137], v[140:141], v[136:137]
	v_lshlrev_b32_e32 v140, 16, v142
	v_and_b32_e32 v141, 0xffff0000, v142
	v_max_f32_e32 v140, 0x1e3ce508, v140
	v_max_f32_e32 v141, 0x1e3ce508, v141
	v_rcp_f32_e32 v140, v140
	v_rcp_f32_e32 v141, v141
	v_pk_mul_f32 v[14:15], v[14:15], v[136:137]
	v_lshlrev_b32_e32 v136, 16, v138
	v_and_b32_e32 v137, 0xffff0000, v138
	v_lshlrev_b32_e32 v138, 16, v143
	v_max_f32_e32 v138, 0x1e3ce508, v138
	v_pk_mul_f32 v[136:137], v[140:141], v[136:137]
	v_rcp_f32_e32 v140, v138
	v_and_b32_e32 v138, 0xffff0000, v143
	v_max_f32_e32 v138, 0x1e3ce508, v138
	v_rcp_f32_e32 v141, v138
	v_pk_mul_f32 v[8:9], v[8:9], v[136:137]
	v_lshlrev_b32_e32 v136, 16, v139
	v_and_b32_e32 v137, 0xffff0000, v139
	v_pk_mul_f32 v[136:137], v[140:141], v[136:137]
	s_waitcnt vmcnt(0)
	v_lshlrev_b32_e32 v138, 16, v132
	v_and_b32_e32 v132, 0xffff0000, v132
	v_pk_mul_f32 v[10:11], v[10:11], v[136:137]
	v_lshlrev_b32_e32 v136, 16, v128
	v_and_b32_e32 v137, 0xffff0000, v128
	v_lshlrev_b32_e32 v128, 16, v133
	v_max_f32_e32 v132, 0x1e3ce508, v132
	v_max_f32_e32 v128, 0x1e3ce508, v128
	v_rcp_f32_e32 v139, v132
	v_rcp_f32_e32 v132, v128
	v_and_b32_e32 v128, 0xffff0000, v133
	v_max_f32_e32 v128, 0x1e3ce508, v128
	v_rcp_f32_e32 v133, v128
	v_lshlrev_b32_e32 v128, 16, v129
	v_and_b32_e32 v129, 0xffff0000, v129
	v_pk_mul_f32 v[128:129], v[132:133], v[128:129]
	v_lshlrev_b32_e32 v132, 16, v134
	v_and_b32_e32 v133, 0xffff0000, v134
	v_max_f32_e32 v132, 0x1e3ce508, v132
	v_max_f32_e32 v133, 0x1e3ce508, v133
	v_rcp_f32_e32 v132, v132
	v_rcp_f32_e32 v133, v133
	v_pk_mul_f32 v[6:7], v[6:7], v[128:129]
	v_lshlrev_b32_e32 v128, 16, v130
	v_and_b32_e32 v129, 0xffff0000, v130
	v_lshlrev_b32_e32 v130, 16, v135
	v_max_f32_e32 v130, 0x1e3ce508, v130
	v_pk_mul_f32 v[128:129], v[132:133], v[128:129]
	v_rcp_f32_e32 v132, v130
	v_and_b32_e32 v130, 0xffff0000, v135
	v_max_f32_e32 v190, 0x1e3ce508, v190
	v_max_f32_e32 v162, 0x1e3ce508, v162
	v_max_f32_e32 v154, 0x1e3ce508, v154
	v_max_f32_e32 v146, 0x1e3ce508, v146
	v_max_f32_e32 v138, 0x1e3ce508, v138
	v_max_f32_e32 v130, 0x1e3ce508, v130
	v_rcp_f32_e32 v190, v190
	v_rcp_f32_e32 v162, v162
	v_rcp_f32_e32 v154, v154
	v_rcp_f32_e32 v146, v146
	v_rcp_f32_e32 v138, v138
	v_rcp_f32_e32 v133, v130
	v_pk_mul_f32 v[0:1], v[0:1], v[128:129]
	v_lshlrev_b32_e32 v128, 16, v131
	v_and_b32_e32 v129, 0xffff0000, v131
	v_pk_mul_f32 v[188:189], v[190:191], v[188:189]
	v_pk_mul_f32 v[160:161], v[162:163], v[160:161]
	v_pk_mul_f32 v[152:153], v[154:155], v[152:153]
	v_pk_mul_f32 v[144:145], v[146:147], v[144:145]
	v_pk_mul_f32 v[136:137], v[138:139], v[136:137]
	v_pk_mul_f32 v[128:129], v[132:133], v[128:129]
	v_pk_mul_f32 v[36:37], v[36:37], v[188:189]
	v_pk_mul_f32 v[28:29], v[28:29], v[160:161]
	v_pk_mul_f32 v[20:21], v[20:21], v[152:153]
	v_pk_mul_f32 v[12:13], v[12:13], v[144:145]
	v_pk_mul_f32 v[4:5], v[4:5], v[136:137]
	v_pk_mul_f32 v[2:3], v[2:3], v[128:129]
	s_branch .LBB0_1003

.LBB0_1012:
	v_or_b32_e32 v128, s57, v196
	v_add_u32_e32 v146, s56, v194
	v_ashrrev_i32_e32 v129, 31, v128
	v_mov_b64_e32 v[148:149], s[10:11]
	v_mad_i64_i32 v[130:131], s[24:25], v146, s49, v[148:149]
	v_lshlrev_b64 v[144:145], 1, v[128:129]
	v_lshl_add_u64 v[128:129], v[130:131], 0, v[144:145]
	v_lshl_add_u64 v[130:131], v[128:129], 0, s[20:21]
	v_add_co_u32_e32 v128, vcc, 0x1000, v128
	v_or_b32_e32 v184, 16, v146
	s_nop 0
	v_addc_co_u32_e32 v129, vcc, 0, v129, vcc
	global_load_dwordx4 v[152:155], v[128:129], off offset:3584
	global_load_dwordx4 v[156:159], v[130:131], off offset:256
	v_mad_i64_i32 v[128:129], s[24:25], v184, s49, v[148:149]
	v_lshl_add_u64 v[128:129], v[128:129], 0, v[144:145]
	v_lshl_add_u64 v[130:131], v[128:129], 0, s[20:21]
	v_add_co_u32_e32 v128, vcc, 0x1000, v128
	v_or_b32_e32 v186, 32, v146
	s_nop 0
	v_addc_co_u32_e32 v129, vcc, 0, v129, vcc
	global_load_dwordx4 v[160:163], v[128:129], off offset:3584
	global_load_dwordx4 v[164:167], v[130:131], off offset:256
	v_mad_i64_i32 v[128:129], s[24:25], v186, s49, v[148:149]
	v_lshl_add_u64 v[128:129], v[128:129], 0, v[144:145]
	v_lshl_add_u64 v[130:131], v[128:129], 0, s[20:21]
	v_add_co_u32_e32 v128, vcc, 0x1000, v128
	v_or_b32_e32 v150, 48, v146
	s_nop 0
	v_addc_co_u32_e32 v129, vcc, 0, v129, vcc
	global_load_dwordx4 v[140:143], v[128:129], off offset:3584
	global_load_dwordx4 v[136:139], v[130:131], off offset:256
	v_mad_i64_i32 v[128:129], s[24:25], v150, s49, v[148:149]
	v_lshl_add_u64 v[128:129], v[128:129], 0, v[144:145]
	v_lshl_add_u64 v[130:131], v[128:129], 0, s[20:21]
	v_add_co_u32_e32 v128, vcc, 0x1000, v128
	v_ashrrev_i32_e32 v147, 31, v146
	s_nop 0
	v_addc_co_u32_e32 v129, vcc, 0, v129, vcc
	global_load_dwordx4 v[132:135], v[128:129], off offset:3584
	s_nop 0
	global_load_dwordx4 v[128:131], v[130:131], off offset:256
	v_ashrrev_i32_e32 v185, 31, v184
	v_ashrrev_i32_e32 v187, 31, v186
	v_ashrrev_i32_e32 v151, 31, v150
	v_lshlrev_b64 v[188:189], 11, v[146:147]
	s_waitcnt vmcnt(0)
	v_lshlrev_b32_e32 v147, 16, v152
	v_max_f32_e32 v147, v147, v147
	v_max_f32_e32 v190, 0x1e3ce508, v147
	v_and_b32_e32 v147, 0xffff0000, v152
	v_max_f32_e32 v147, v147, v147
	v_max_f32_e32 v191, 0x1e3ce508, v147
	v_lshlrev_b32_e32 v147, 16, v154
	v_max_f32_e32 v147, v147, v147
	v_pk_mul_f32 v[124:125], v[124:125], v[190:191]
	v_max_f32_e32 v190, 0x1e3ce508, v147
	v_and_b32_e32 v147, 0xffff0000, v154
	v_max_f32_e32 v147, v147, v147
	v_max_f32_e32 v191, 0x1e3ce508, v147
	v_pk_mul_f32 v[190:191], v[120:121], v[190:191]
	v_lshlrev_b32_e32 v120, 16, v153
	v_and_b32_e32 v121, 0xffff0000, v153
	v_max_f32_e32 v120, 0x1e3ce508, v120
	v_max_f32_e32 v121, 0x1e3ce508, v121
	v_pk_mul_f32 v[126:127], v[126:127], v[120:121]
	v_lshlrev_b32_e32 v120, 16, v155
	v_and_b32_e32 v121, 0xffff0000, v155
	v_max_f32_e32 v120, 0x1e3ce508, v120
	v_max_f32_e32 v121, 0x1e3ce508, v121
	v_pk_mul_f32 v[152:153], v[122:123], v[120:121]
	v_cvt_pk_bf16_f32 v120, v124, v125
	v_lshl_add_u64 v[124:125], s[12:13], 0, v[188:189]
	v_cvt_pk_bf16_f32 v121, v126, v127
	v_cvt_pk_bf16_f32 v122, v190, v191
	v_cvt_pk_bf16_f32 v123, v152, v153
	v_lshl_add_u64 v[124:125], v[124:125], 0, v[144:145]
	global_store_dwordx4 v[124:125], v[120:123], off
	s_nop 1
	v_lshlrev_b32_e32 v120, 16, v156
	v_and_b32_e32 v121, 0xffff0000, v156
	v_max_f32_e32 v120, 0x1e3ce508, v120
	v_max_f32_e32 v121, 0x1e3ce508, v121
	v_pk_mul_f32 v[116:117], v[116:117], v[120:121]
	v_lshlrev_b32_e32 v120, 16, v158
	v_and_b32_e32 v121, 0xffff0000, v158
	v_max_f32_e32 v120, 0x1e3ce508, v120
	v_max_f32_e32 v121, 0x1e3ce508, v121
	v_pk_mul_f32 v[120:121], v[112:113], v[120:121]
	v_lshlrev_b32_e32 v112, 16, v157
	v_and_b32_e32 v113, 0xffff0000, v157
	v_max_f32_e32 v112, 0x1e3ce508, v112
	v_max_f32_e32 v113, 0x1e3ce508, v113
	v_pk_mul_f32 v[118:119], v[118:119], v[112:113]
	v_lshlrev_b32_e32 v112, 16, v159
	v_and_b32_e32 v113, 0xffff0000, v159
	v_max_f32_e32 v112, 0x1e3ce508, v112
	v_max_f32_e32 v113, 0x1e3ce508, v113
	v_pk_mul_f32 v[122:123], v[114:115], v[112:113]
	v_cvt_pk_bf16_f32 v112, v116, v117
	v_cvt_pk_bf16_f32 v113, v118, v119
	v_cvt_pk_bf16_f32 v114, v120, v121
	v_cvt_pk_bf16_f32 v115, v122, v123
	global_store_dwordx4 v[124:125], v[112:115], off offset:256
	s_nop 1
	v_lshlrev_b32_e32 v114, 16, v160
	v_and_b32_e32 v115, 0xffff0000, v160
	v_max_f32_e32 v114, 0x1e3ce508, v114
	v_max_f32_e32 v115, 0x1e3ce508, v115
	v_pk_mul_f32 v[108:109], v[108:109], v[114:115]
	v_lshlrev_b32_e32 v114, 16, v162
	v_and_b32_e32 v115, 0xffff0000, v162
	v_max_f32_e32 v114, 0x1e3ce508, v114
	v_max_f32_e32 v115, 0x1e3ce508, v115
	v_pk_mul_f32 v[114:115], v[104:105], v[114:115]
	v_lshlrev_b32_e32 v104, 16, v161
	v_and_b32_e32 v105, 0xffff0000, v161
	v_max_f32_e32 v104, 0x1e3ce508, v104
	v_max_f32_e32 v105, 0x1e3ce508, v105
	v_pk_mul_f32 v[110:111], v[110:111], v[104:105]
	v_lshlrev_b32_e32 v104, 16, v163
	v_and_b32_e32 v105, 0xffff0000, v163
	v_lshlrev_b64 v[112:113], 11, v[184:185]
	v_max_f32_e32 v104, 0x1e3ce508, v104
	v_max_f32_e32 v105, 0x1e3ce508, v105
	v_pk_mul_f32 v[116:117], v[106:107], v[104:105]
	v_cvt_pk_bf16_f32 v104, v108, v109
	v_lshl_add_u64 v[108:109], s[12:13], 0, v[112:113]
	v_cvt_pk_bf16_f32 v105, v110, v111
	v_cvt_pk_bf16_f32 v106, v114, v115
	v_cvt_pk_bf16_f32 v107, v116, v117
	v_lshl_add_u64 v[108:109], v[108:109], 0, v[144:145]
	global_store_dwordx4 v[108:109], v[104:107], off
	s_nop 1
	v_lshlrev_b32_e32 v104, 16, v164
	v_and_b32_e32 v105, 0xffff0000, v164
	v_max_f32_e32 v104, 0x1e3ce508, v104
	v_max_f32_e32 v105, 0x1e3ce508, v105
	v_pk_mul_f32 v[100:101], v[100:101], v[104:105]
	v_lshlrev_b32_e32 v104, 16, v166
	v_and_b32_e32 v105, 0xffff0000, v166
	v_max_f32_e32 v104, 0x1e3ce508, v104
	v_max_f32_e32 v105, 0x1e3ce508, v105
	v_pk_mul_f32 v[104:105], v[96:97], v[104:105]
	v_lshlrev_b32_e32 v96, 16, v165
	v_and_b32_e32 v97, 0xffff0000, v165
	v_max_f32_e32 v96, 0x1e3ce508, v96
	v_max_f32_e32 v97, 0x1e3ce508, v97
	v_pk_mul_f32 v[102:103], v[102:103], v[96:97]
	v_lshlrev_b32_e32 v96, 16, v167
	v_and_b32_e32 v97, 0xffff0000, v167
	v_max_f32_e32 v96, 0x1e3ce508, v96
	v_max_f32_e32 v97, 0x1e3ce508, v97
	v_pk_mul_f32 v[106:107], v[98:99], v[96:97]
	v_cvt_pk_bf16_f32 v96, v100, v101
	v_cvt_pk_bf16_f32 v97, v102, v103
	v_cvt_pk_bf16_f32 v98, v104, v105
	v_cvt_pk_bf16_f32 v99, v106, v107
	global_store_dwordx4 v[108:109], v[96:99], off offset:256
	s_nop 1
	v_lshlrev_b32_e32 v98, 16, v140
	v_and_b32_e32 v99, 0xffff0000, v140
	v_max_f32_e32 v98, 0x1e3ce508, v98
	v_max_f32_e32 v99, 0x1e3ce508, v99
	v_pk_mul_f32 v[92:93], v[92:93], v[98:99]
	v_lshlrev_b32_e32 v98, 16, v142
	v_and_b32_e32 v99, 0xffff0000, v142
	v_max_f32_e32 v98, 0x1e3ce508, v98
	v_max_f32_e32 v99, 0x1e3ce508, v99
	v_pk_mul_f32 v[98:99], v[88:89], v[98:99]
	v_lshlrev_b32_e32 v88, 16, v141
	v_and_b32_e32 v89, 0xffff0000, v141
	v_max_f32_e32 v88, 0x1e3ce508, v88
	v_max_f32_e32 v89, 0x1e3ce508, v89
	v_pk_mul_f32 v[94:95], v[94:95], v[88:89]
	v_lshlrev_b32_e32 v88, 16, v143
	v_and_b32_e32 v89, 0xffff0000, v143
	v_lshlrev_b64 v[96:97], 11, v[186:187]
	v_max_f32_e32 v88, 0x1e3ce508, v88
	v_max_f32_e32 v89, 0x1e3ce508, v89
	v_pk_mul_f32 v[100:101], v[90:91], v[88:89]
	v_cvt_pk_bf16_f32 v88, v92, v93
	v_lshl_add_u64 v[92:93], s[12:13], 0, v[96:97]
	v_cvt_pk_bf16_f32 v89, v94, v95
	v_cvt_pk_bf16_f32 v90, v98, v99
	v_cvt_pk_bf16_f32 v91, v100, v101
	v_lshl_add_u64 v[92:93], v[92:93], 0, v[144:145]
	global_store_dwordx4 v[92:93], v[88:91], off
	s_nop 1
	v_lshlrev_b32_e32 v88, 16, v136
	v_and_b32_e32 v89, 0xffff0000, v136
	v_max_f32_e32 v88, 0x1e3ce508, v88
	v_max_f32_e32 v89, 0x1e3ce508, v89
	v_pk_mul_f32 v[84:85], v[84:85], v[88:89]
	v_lshlrev_b32_e32 v88, 16, v138
	v_and_b32_e32 v89, 0xffff0000, v138
	v_max_f32_e32 v88, 0x1e3ce508, v88
	v_max_f32_e32 v89, 0x1e3ce508, v89
	v_pk_mul_f32 v[88:89], v[80:81], v[88:89]
	v_lshlrev_b32_e32 v80, 16, v137
	v_and_b32_e32 v81, 0xffff0000, v137
	v_max_f32_e32 v80, 0x1e3ce508, v80
	v_max_f32_e32 v81, 0x1e3ce508, v81
	v_pk_mul_f32 v[86:87], v[86:87], v[80:81]
	v_lshlrev_b32_e32 v80, 16, v139
	v_and_b32_e32 v81, 0xffff0000, v139
	v_max_f32_e32 v80, 0x1e3ce508, v80
	v_max_f32_e32 v81, 0x1e3ce508, v81
	v_pk_mul_f32 v[90:91], v[82:83], v[80:81]
	v_cvt_pk_bf16_f32 v80, v84, v85
	v_cvt_pk_bf16_f32 v81, v86, v87
	v_cvt_pk_bf16_f32 v82, v88, v89
	v_cvt_pk_bf16_f32 v83, v90, v91
	global_store_dwordx4 v[92:93], v[80:83], off offset:256
	s_nop 1
	v_lshlrev_b32_e32 v82, 16, v132
	v_and_b32_e32 v83, 0xffff0000, v132
	v_max_f32_e32 v82, 0x1e3ce508, v82
	v_max_f32_e32 v83, 0x1e3ce508, v83
	v_pk_mul_f32 v[76:77], v[76:77], v[82:83]
	v_lshlrev_b32_e32 v82, 16, v134
	v_and_b32_e32 v83, 0xffff0000, v134
	v_max_f32_e32 v82, 0x1e3ce508, v82
	v_max_f32_e32 v83, 0x1e3ce508, v83
	v_pk_mul_f32 v[82:83], v[72:73], v[82:83]
	v_lshlrev_b32_e32 v72, 16, v133
	v_and_b32_e32 v73, 0xffff0000, v133
	v_max_f32_e32 v72, 0x1e3ce508, v72
	v_max_f32_e32 v73, 0x1e3ce508, v73
	v_pk_mul_f32 v[78:79], v[78:79], v[72:73]
	v_lshlrev_b32_e32 v72, 16, v135
	v_and_b32_e32 v73, 0xffff0000, v135
	v_lshlrev_b64 v[80:81], 11, v[150:151]
	v_max_f32_e32 v72, 0x1e3ce508, v72
	v_max_f32_e32 v73, 0x1e3ce508, v73
	v_pk_mul_f32 v[84:85], v[74:75], v[72:73]
	v_cvt_pk_bf16_f32 v72, v76, v77
	v_lshl_add_u64 v[76:77], s[12:13], 0, v[80:81]
	v_cvt_pk_bf16_f32 v73, v78, v79
	v_cvt_pk_bf16_f32 v74, v82, v83
	v_cvt_pk_bf16_f32 v75, v84, v85
	v_lshl_add_u64 v[76:77], v[76:77], 0, v[144:145]
	global_store_dwordx4 v[76:77], v[72:75], off
	s_nop 1
	v_lshlrev_b32_e32 v72, 16, v128
	v_and_b32_e32 v73, 0xffff0000, v128
	v_max_f32_e32 v72, 0x1e3ce508, v72
	v_max_f32_e32 v73, 0x1e3ce508, v73
	v_pk_mul_f32 v[68:69], v[68:69], v[72:73]
	v_lshlrev_b32_e32 v72, 16, v130
	v_and_b32_e32 v73, 0xffff0000, v130
	v_max_f32_e32 v72, 0x1e3ce508, v72
	v_max_f32_e32 v73, 0x1e3ce508, v73
	v_pk_mul_f32 v[72:73], v[64:65], v[72:73]
	v_lshlrev_b32_e32 v64, 16, v129
	v_and_b32_e32 v65, 0xffff0000, v129
	v_max_f32_e32 v64, 0x1e3ce508, v64
	v_max_f32_e32 v65, 0x1e3ce508, v65
	v_pk_mul_f32 v[70:71], v[70:71], v[64:65]
	v_lshlrev_b32_e32 v64, 16, v131
	v_and_b32_e32 v65, 0xffff0000, v131
	v_max_f32_e32 v64, 0x1e3ce508, v64
	v_max_f32_e32 v65, 0x1e3ce508, v65
	v_pk_mul_f32 v[74:75], v[66:67], v[64:65]
	v_cvt_pk_bf16_f32 v64, v68, v69
	v_cvt_pk_bf16_f32 v65, v70, v71
	v_cvt_pk_bf16_f32 v66, v72, v73
	v_cvt_pk_bf16_f32 v67, v74, v75
	global_store_dwordx4 v[76:77], v[64:67], off offset:256
	v_add_u32_e32 v98, 0x80, v146
	s_nop 0
	v_mad_i64_i32 v[64:65], s[24:25], v98, s49, v[148:149]
	v_lshl_add_u64 v[64:65], v[64:65], 0, v[144:145]
	v_lshl_add_u64 v[66:67], v[64:65], 0, s[20:21]
	v_add_co_u32_e32 v64, vcc, s52, v64
	v_add_u32_e32 v100, 0x90, v146
	s_nop 0
	v_addc_co_u32_e32 v65, vcc, 0, v65, vcc
	global_load_dwordx4 v[82:85], v[64:65], off offset:3584
	global_load_dwordx4 v[86:89], v[66:67], off offset:256
	v_mad_i64_i32 v[64:65], s[24:25], v100, s49, v[148:149]
	v_lshl_add_u64 v[64:65], v[64:65], 0, v[144:145]
	v_lshl_add_u64 v[66:67], v[64:65], 0, s[20:21]
	v_add_co_u32_e32 v64, vcc, s52, v64
	v_add_u32_e32 v102, 0xa0, v146
	s_nop 0
	v_addc_co_u32_e32 v65, vcc, 0, v65, vcc
	global_load_dwordx4 v[90:93], v[64:65], off offset:3584
	global_load_dwordx4 v[94:97], v[66:67], off offset:256
	v_mad_i64_i32 v[64:65], s[24:25], v102, s49, v[148:149]
	v_lshl_add_u64 v[64:65], v[64:65], 0, v[144:145]
	v_lshl_add_u64 v[66:67], v[64:65], 0, s[20:21]
	v_add_co_u32_e32 v64, vcc, s52, v64
	v_add_u32_e32 v80, 0xb0, v146
	s_nop 0
	v_addc_co_u32_e32 v65, vcc, 0, v65, vcc
	global_load_dwordx4 v[76:79], v[64:65], off offset:3584
	global_load_dwordx4 v[72:75], v[66:67], off offset:256
	v_mad_i64_i32 v[64:65], s[24:25], v80, s49, v[148:149]
	v_lshl_add_u64 v[64:65], v[64:65], 0, v[144:145]
	v_lshl_add_u64 v[66:67], v[64:65], 0, s[20:21]
	v_add_co_u32_e32 v64, vcc, s52, v64
	v_ashrrev_i32_e32 v99, 31, v98
	s_nop 0
	v_addc_co_u32_e32 v65, vcc, 0, v65, vcc
	global_load_dwordx4 v[68:71], v[64:65], off offset:3584
	s_nop 0
	global_load_dwordx4 v[64:67], v[66:67], off offset:256
	v_ashrrev_i32_e32 v101, 31, v100
	v_ashrrev_i32_e32 v103, 31, v102
	v_ashrrev_i32_e32 v81, 31, v80
	s_waitcnt vmcnt(7)
	v_lshlrev_b32_e32 v104, 16, v82
	v_and_b32_e32 v82, 0xffff0000, v82
	v_max_f32_e32 v82, v82, v82
	v_max_f32_e32 v105, 0x1e3ce508, v82
	v_lshlrev_b32_e32 v82, 16, v84
	v_max_f32_e32 v104, 0x1e3ce508, v104
	v_max_f32_e32 v82, v82, v82
	v_pk_mul_f32 v[60:61], v[60:61], v[104:105]
	v_max_f32_e32 v104, 0x1e3ce508, v82
	v_and_b32_e32 v82, 0xffff0000, v84
	v_max_f32_e32 v82, v82, v82
	v_max_f32_e32 v105, 0x1e3ce508, v82
	v_pk_mul_f32 v[104:105], v[56:57], v[104:105]
	v_lshlrev_b32_e32 v56, 16, v83
	v_and_b32_e32 v57, 0xffff0000, v83
	v_max_f32_e32 v56, 0x1e3ce508, v56
	v_max_f32_e32 v57, 0x1e3ce508, v57
	v_pk_mul_f32 v[62:63], v[62:63], v[56:57]
	v_lshlrev_b32_e32 v56, 16, v85
	v_and_b32_e32 v57, 0xffff0000, v85
	v_lshlrev_b64 v[98:99], 11, v[98:99]
	v_max_f32_e32 v56, 0x1e3ce508, v56
	v_max_f32_e32 v57, 0x1e3ce508, v57
	v_pk_mul_f32 v[82:83], v[58:59], v[56:57]
	v_cvt_pk_bf16_f32 v56, v60, v61
	v_lshl_add_u64 v[60:61], s[12:13], 0, v[98:99]
	v_cvt_pk_bf16_f32 v57, v62, v63
	v_cvt_pk_bf16_f32 v58, v104, v105
	v_cvt_pk_bf16_f32 v59, v82, v83
	v_lshl_add_u64 v[60:61], v[60:61], 0, v[144:145]
	global_store_dwordx4 v[60:61], v[56:59], off
	s_waitcnt vmcnt(7)
	s_nop 0
	v_lshlrev_b32_e32 v56, 16, v86
	v_and_b32_e32 v57, 0xffff0000, v86
	v_max_f32_e32 v56, 0x1e3ce508, v56
	v_max_f32_e32 v57, 0x1e3ce508, v57
	v_pk_mul_f32 v[52:53], v[52:53], v[56:57]
	v_lshlrev_b32_e32 v56, 16, v88
	v_and_b32_e32 v57, 0xffff0000, v88
	v_max_f32_e32 v56, 0x1e3ce508, v56
	v_max_f32_e32 v57, 0x1e3ce508, v57
	v_pk_mul_f32 v[56:57], v[48:49], v[56:57]
	v_lshlrev_b32_e32 v48, 16, v87
	v_and_b32_e32 v49, 0xffff0000, v87
	v_max_f32_e32 v48, 0x1e3ce508, v48
	v_max_f32_e32 v49, 0x1e3ce508, v49
	v_pk_mul_f32 v[54:55], v[54:55], v[48:49]
	v_lshlrev_b32_e32 v48, 16, v89
	v_and_b32_e32 v49, 0xffff0000, v89
	v_max_f32_e32 v48, 0x1e3ce508, v48
	v_max_f32_e32 v49, 0x1e3ce508, v49
	v_pk_mul_f32 v[58:59], v[50:51], v[48:49]
	v_cvt_pk_bf16_f32 v48, v52, v53
	v_cvt_pk_bf16_f32 v49, v54, v55
	v_cvt_pk_bf16_f32 v50, v56, v57
	v_cvt_pk_bf16_f32 v51, v58, v59
	global_store_dwordx4 v[60:61], v[48:51], off offset:256
	s_waitcnt vmcnt(7)
	s_nop 0
	v_lshlrev_b32_e32 v50, 16, v90
	v_and_b32_e32 v51, 0xffff0000, v90
	v_max_f32_e32 v50, 0x1e3ce508, v50
	v_max_f32_e32 v51, 0x1e3ce508, v51
	v_pk_mul_f32 v[44:45], v[44:45], v[50:51]
	v_lshlrev_b32_e32 v50, 16, v92
	v_and_b32_e32 v51, 0xffff0000, v92
	v_max_f32_e32 v50, 0x1e3ce508, v50
	v_max_f32_e32 v51, 0x1e3ce508, v51
	v_pk_mul_f32 v[50:51], v[40:41], v[50:51]
	v_lshlrev_b32_e32 v40, 16, v91
	v_and_b32_e32 v41, 0xffff0000, v91
	v_max_f32_e32 v40, 0x1e3ce508, v40
	v_max_f32_e32 v41, 0x1e3ce508, v41
	v_pk_mul_f32 v[46:47], v[46:47], v[40:41]
	v_lshlrev_b32_e32 v40, 16, v93
	v_and_b32_e32 v41, 0xffff0000, v93
	v_lshlrev_b64 v[48:49], 11, v[100:101]
	v_max_f32_e32 v40, 0x1e3ce508, v40
	v_max_f32_e32 v41, 0x1e3ce508, v41
	v_pk_mul_f32 v[52:53], v[42:43], v[40:41]
	v_cvt_pk_bf16_f32 v40, v44, v45
	v_lshl_add_u64 v[44:45], s[12:13], 0, v[48:49]
	v_cvt_pk_bf16_f32 v41, v46, v47
	v_cvt_pk_bf16_f32 v42, v50, v51
	v_cvt_pk_bf16_f32 v43, v52, v53
	v_lshl_add_u64 v[44:45], v[44:45], 0, v[144:145]
	global_store_dwordx4 v[44:45], v[40:43], off
	s_waitcnt vmcnt(7)
	s_nop 0
	v_lshlrev_b32_e32 v40, 16, v94
	v_and_b32_e32 v41, 0xffff0000, v94
	v_max_f32_e32 v40, 0x1e3ce508, v40
	v_max_f32_e32 v41, 0x1e3ce508, v41
	v_pk_mul_f32 v[36:37], v[36:37], v[40:41]
	v_lshlrev_b32_e32 v40, 16, v96
	v_and_b32_e32 v41, 0xffff0000, v96
	v_max_f32_e32 v40, 0x1e3ce508, v40
	v_max_f32_e32 v41, 0x1e3ce508, v41
	v_pk_mul_f32 v[40:41], v[32:33], v[40:41]
	v_lshlrev_b32_e32 v32, 16, v95
	v_and_b32_e32 v33, 0xffff0000, v95
	v_max_f32_e32 v32, 0x1e3ce508, v32
	v_max_f32_e32 v33, 0x1e3ce508, v33
	v_pk_mul_f32 v[38:39], v[38:39], v[32:33]
	v_lshlrev_b32_e32 v32, 16, v97
	v_and_b32_e32 v33, 0xffff0000, v97
	v_max_f32_e32 v32, 0x1e3ce508, v32
	v_max_f32_e32 v33, 0x1e3ce508, v33
	v_pk_mul_f32 v[42:43], v[34:35], v[32:33]
	v_cvt_pk_bf16_f32 v32, v36, v37
	v_cvt_pk_bf16_f32 v33, v38, v39
	v_cvt_pk_bf16_f32 v34, v40, v41
	v_cvt_pk_bf16_f32 v35, v42, v43
	global_store_dwordx4 v[44:45], v[32:35], off offset:256
	s_waitcnt vmcnt(7)
	s_nop 0
	v_lshlrev_b32_e32 v34, 16, v76
	v_and_b32_e32 v35, 0xffff0000, v76
	v_max_f32_e32 v34, 0x1e3ce508, v34
	v_max_f32_e32 v35, 0x1e3ce508, v35
	v_pk_mul_f32 v[28:29], v[28:29], v[34:35]
	v_lshlrev_b32_e32 v34, 16, v78
	v_and_b32_e32 v35, 0xffff0000, v78
	v_max_f32_e32 v34, 0x1e3ce508, v34
	v_max_f32_e32 v35, 0x1e3ce508, v35
	v_pk_mul_f32 v[34:35], v[24:25], v[34:35]
	v_lshlrev_b32_e32 v24, 16, v77
	v_and_b32_e32 v25, 0xffff0000, v77
	v_max_f32_e32 v24, 0x1e3ce508, v24
	v_max_f32_e32 v25, 0x1e3ce508, v25
	v_pk_mul_f32 v[30:31], v[30:31], v[24:25]
	v_lshlrev_b32_e32 v24, 16, v79
	v_and_b32_e32 v25, 0xffff0000, v79
	v_lshlrev_b64 v[32:33], 11, v[102:103]
	v_max_f32_e32 v24, 0x1e3ce508, v24
	v_max_f32_e32 v25, 0x1e3ce508, v25
	v_pk_mul_f32 v[36:37], v[26:27], v[24:25]
	v_cvt_pk_bf16_f32 v24, v28, v29
	v_lshl_add_u64 v[28:29], s[12:13], 0, v[32:33]
	v_cvt_pk_bf16_f32 v25, v30, v31
	v_cvt_pk_bf16_f32 v26, v34, v35
	v_cvt_pk_bf16_f32 v27, v36, v37
	v_lshl_add_u64 v[28:29], v[28:29], 0, v[144:145]
	global_store_dwordx4 v[28:29], v[24:27], off
	s_waitcnt vmcnt(7)
	s_nop 0
	v_lshlrev_b32_e32 v24, 16, v72
	v_and_b32_e32 v25, 0xffff0000, v72
	v_max_f32_e32 v24, 0x1e3ce508, v24
	v_max_f32_e32 v25, 0x1e3ce508, v25
	v_pk_mul_f32 v[20:21], v[20:21], v[24:25]
	v_lshlrev_b32_e32 v24, 16, v74
	v_and_b32_e32 v25, 0xffff0000, v74
	v_max_f32_e32 v24, 0x1e3ce508, v24
	v_max_f32_e32 v25, 0x1e3ce508, v25
	v_pk_mul_f32 v[24:25], v[16:17], v[24:25]
	v_lshlrev_b32_e32 v16, 16, v73
	v_and_b32_e32 v17, 0xffff0000, v73
	v_max_f32_e32 v16, 0x1e3ce508, v16
	v_max_f32_e32 v17, 0x1e3ce508, v17
	v_pk_mul_f32 v[22:23], v[22:23], v[16:17]
	v_lshlrev_b32_e32 v16, 16, v75
	v_and_b32_e32 v17, 0xffff0000, v75
	v_max_f32_e32 v16, 0x1e3ce508, v16
	v_max_f32_e32 v17, 0x1e3ce508, v17
	v_pk_mul_f32 v[26:27], v[18:19], v[16:17]
	v_cvt_pk_bf16_f32 v16, v20, v21
	v_cvt_pk_bf16_f32 v17, v22, v23
	v_cvt_pk_bf16_f32 v18, v24, v25
	v_cvt_pk_bf16_f32 v19, v26, v27
	global_store_dwordx4 v[28:29], v[16:19], off offset:256
	s_waitcnt vmcnt(7)
	s_nop 0
	v_lshlrev_b32_e32 v18, 16, v68
	v_and_b32_e32 v19, 0xffff0000, v68
	v_max_f32_e32 v18, 0x1e3ce508, v18
	v_max_f32_e32 v19, 0x1e3ce508, v19
	v_pk_mul_f32 v[12:13], v[12:13], v[18:19]
	v_lshlrev_b32_e32 v18, 16, v70
	v_and_b32_e32 v19, 0xffff0000, v70
	v_max_f32_e32 v18, 0x1e3ce508, v18
	v_max_f32_e32 v19, 0x1e3ce508, v19
	v_pk_mul_f32 v[18:19], v[8:9], v[18:19]
	v_lshlrev_b32_e32 v8, 16, v69
	v_and_b32_e32 v9, 0xffff0000, v69
	v_max_f32_e32 v8, 0x1e3ce508, v8
	v_max_f32_e32 v9, 0x1e3ce508, v9
	v_pk_mul_f32 v[14:15], v[14:15], v[8:9]
	v_lshlrev_b32_e32 v8, 16, v71
	v_and_b32_e32 v9, 0xffff0000, v71
	v_lshlrev_b64 v[16:17], 11, v[80:81]
	v_max_f32_e32 v8, 0x1e3ce508, v8
	v_max_f32_e32 v9, 0x1e3ce508, v9
	v_pk_mul_f32 v[20:21], v[10:11], v[8:9]
	v_cvt_pk_bf16_f32 v8, v12, v13
	v_lshl_add_u64 v[12:13], s[12:13], 0, v[16:17]
	v_cvt_pk_bf16_f32 v9, v14, v15
	v_cvt_pk_bf16_f32 v10, v18, v19
	v_cvt_pk_bf16_f32 v11, v20, v21
	v_lshl_add_u64 v[12:13], v[12:13], 0, v[144:145]
	global_store_dwordx4 v[12:13], v[8:11], off
	s_waitcnt vmcnt(7)
	s_nop 0
	v_lshlrev_b32_e32 v8, 16, v64
	v_and_b32_e32 v9, 0xffff0000, v64
	v_max_f32_e32 v8, 0x1e3ce508, v8
	v_max_f32_e32 v9, 0x1e3ce508, v9
	v_pk_mul_f32 v[4:5], v[4:5], v[8:9]
	v_lshlrev_b32_e32 v8, 16, v66
	v_and_b32_e32 v9, 0xffff0000, v66
	v_max_f32_e32 v8, 0x1e3ce508, v8
	v_max_f32_e32 v9, 0x1e3ce508, v9
	v_pk_mul_f32 v[8:9], v[0:1], v[8:9]
	v_lshlrev_b32_e32 v0, 16, v65
	v_and_b32_e32 v1, 0xffff0000, v65
	v_max_f32_e32 v0, 0x1e3ce508, v0
	v_max_f32_e32 v1, 0x1e3ce508, v1
	v_pk_mul_f32 v[6:7], v[6:7], v[0:1]
	v_lshlrev_b32_e32 v0, 16, v67
	v_and_b32_e32 v1, 0xffff0000, v67
	v_max_f32_e32 v0, 0x1e3ce508, v0
	v_max_f32_e32 v1, 0x1e3ce508, v1
	v_pk_mul_f32 v[10:11], v[2:3], v[0:1]
	v_cvt_pk_bf16_f32 v0, v4, v5
	v_cvt_pk_bf16_f32 v1, v6, v7
	v_cvt_pk_bf16_f32 v2, v8, v9
	v_cvt_pk_bf16_f32 v3, v10, v11
	global_store_dwordx4 v[12:13], v[0:3], off offset:256
	s_and_b64 vcc, exec, s[2:3]
	s_mov_b64 s[2:3], -1
	s_cbranch_vccnz .LBB0_991
	s_andn2_b64 vcc, exec, s[8:9]
	s_cbranch_vccnz .LBB0_990
	v_writelane_b32 v255, 1, 53
	s_branch .LBB0_990

.LBB0_2160:
	s_andn2_b64 vcc, exec, s[28:29]
	s_cbranch_vccnz .LBB0_2155
	v_mov_b32_e32 v128, v193
	v_mov_b32_e32 v129, v192
	s_and_b32 s6, s26, 0xc00
	v_add_u32_e32 v198, s59, v129
	v_mov_b64_e32 v[188:189], s[10:11]
	v_lshl_add_u32 v128, v128, 3, s58
	s_addk_i32 s6, 0xfc00
	v_mad_i64_i32 v[130:131], s[28:29], v198, s49, v[188:189]
	v_ashrrev_i32_e32 v129, 31, v128
	s_lshl_b64 s[28:29], s[6:7], 1
	v_lshl_add_u64 v[130:131], v[130:131], 0, s[28:29]
	v_lshlrev_b64 v[190:191], 1, v[128:129]
	v_lshl_add_u64 v[128:129], v[130:131], 0, v[190:191]
	v_lshl_add_u64 v[130:131], v[128:129], 0, s[18:19]
	global_load_dwordx4 v[200:203], v[128:129], off offset:3584
	global_load_dwordx4 v[206:209], v[128:129], off offset:3840
	global_load_dwordx4 v[210:213], v[130:131], off offset:2048
	global_load_dwordx4 v[214:217], v[130:131], off offset:2304
	v_add_u32_e32 v128, 16, v198
	v_mad_i64_i32 v[128:129], s[30:31], v128, s49, v[188:189]
	v_lshl_add_u64 v[128:129], v[128:129], 0, s[28:29]
	v_lshl_add_u64 v[128:129], v[128:129], 0, v[190:191]
	v_lshl_add_u64 v[130:131], v[128:129], 0, s[18:19]
	global_load_dwordx4 v[218:221], v[128:129], off offset:3584
	global_load_dwordx4 v[160:163], v[128:129], off offset:3840
	global_load_dwordx4 v[222:225], v[130:131], off offset:2048
	global_load_dwordx4 v[164:167], v[130:131], off offset:2304
	v_add_u32_e32 v128, 32, v198
	v_mad_i64_i32 v[128:129], s[30:31], v128, s49, v[188:189]
	v_lshl_add_u64 v[128:129], v[128:129], 0, s[28:29]
	v_lshl_add_u64 v[128:129], v[128:129], 0, v[190:191]
	v_lshl_add_u64 v[130:131], v[128:129], 0, s[18:19]
	global_load_dwordx4 v[152:155], v[128:129], off offset:3584
	global_load_dwordx4 v[144:147], v[128:129], off offset:3840
	global_load_dwordx4 v[156:159], v[130:131], off offset:2048
	global_load_dwordx4 v[148:151], v[130:131], off offset:2304
	v_add_u32_e32 v128, 48, v198
	v_mad_i64_i32 v[128:129], s[30:31], v128, s49, v[188:189]
	v_lshl_add_u64 v[128:129], v[128:129], 0, s[28:29]
	v_lshl_add_u64 v[128:129], v[128:129], 0, v[190:191]
	v_lshl_add_u64 v[132:133], v[128:129], 0, s[18:19]
	global_load_dwordx4 v[136:139], v[128:129], off offset:3584
	s_nop 0
	global_load_dwordx4 v[128:131], v[128:129], off offset:3840
	s_nop 0
	global_load_dwordx4 v[140:143], v[132:133], off offset:2048
	s_nop 0
	global_load_dwordx4 v[132:135], v[132:133], off offset:2304
	s_waitcnt vmcnt(0)
	v_lshlrev_b32_e32 v199, 16, v210
	v_max_f32_e32 v199, 0x1e3ce508, v199
	v_rcp_f32_e32 v226, v199
	v_and_b32_e32 v199, 0xffff0000, v210
	v_max_f32_e32 v199, 0x1e3ce508, v199
	v_rcp_f32_e32 v227, v199
	v_lshlrev_b32_e32 v199, 16, v211
	v_max_f32_e32 v199, 0x1e3ce508, v199
	v_rcp_f32_e32 v210, v199
	v_and_b32_e32 v199, 0xffff0000, v211
	v_max_f32_e32 v199, 0x1e3ce508, v199
	v_rcp_f32_e32 v211, v199
	v_lshlrev_b32_e32 v199, 16, v212
	v_lshlrev_b32_e32 v228, 16, v200
	v_and_b32_e32 v229, 0xffff0000, v200
	v_lshlrev_b32_e32 v200, 16, v201
	v_and_b32_e32 v201, 0xffff0000, v201
	v_max_f32_e32 v199, 0x1e3ce508, v199
	v_pk_mul_f32 v[200:201], v[210:211], v[200:201]
	v_rcp_f32_e32 v210, v199
	v_and_b32_e32 v199, 0xffff0000, v212
	v_max_f32_e32 v199, 0x1e3ce508, v199
	v_rcp_f32_e32 v211, v199
	v_lshlrev_b32_e32 v199, 16, v213
	v_pk_mul_f32 v[126:127], v[126:127], v[200:201]
	v_lshlrev_b32_e32 v200, 16, v202
	v_and_b32_e32 v201, 0xffff0000, v202
	v_max_f32_e32 v199, 0x1e3ce508, v199
	v_pk_mul_f32 v[200:201], v[210:211], v[200:201]
	v_rcp_f32_e32 v210, v199
	v_and_b32_e32 v199, 0xffff0000, v213
	v_max_f32_e32 v199, 0x1e3ce508, v199
	v_rcp_f32_e32 v211, v199
	v_lshlrev_b32_e32 v199, 16, v214
	v_max_f32_e32 v199, 0x1e3ce508, v199
	v_rcp_f32_e32 v202, v199
	v_and_b32_e32 v199, 0xffff0000, v214
	v_max_f32_e32 v199, 0x1e3ce508, v199
	v_pk_mul_f32 v[120:121], v[120:121], v[200:201]
	v_lshlrev_b32_e32 v200, 16, v203
	v_and_b32_e32 v201, 0xffff0000, v203
	v_rcp_f32_e32 v203, v199
	v_lshlrev_b32_e32 v199, 16, v215
	v_pk_mul_f32 v[200:201], v[210:211], v[200:201]
	v_pk_mul_f32 v[122:123], v[122:123], v[200:201]
	v_lshlrev_b32_e32 v200, 16, v206
	v_and_b32_e32 v201, 0xffff0000, v206
	v_max_f32_e32 v199, 0x1e3ce508, v199
	v_pk_mul_f32 v[200:201], v[202:203], v[200:201]
	v_rcp_f32_e32 v202, v199
	v_and_b32_e32 v199, 0xffff0000, v215
	v_max_f32_e32 v199, 0x1e3ce508, v199
	v_rcp_f32_e32 v203, v199
	v_lshlrev_b32_e32 v199, 16, v216
	v_pk_mul_f32 v[116:117], v[116:117], v[200:201]
	v_lshlrev_b32_e32 v200, 16, v207
	v_and_b32_e32 v201, 0xffff0000, v207
	v_max_f32_e32 v199, 0x1e3ce508, v199
	v_pk_mul_f32 v[200:201], v[202:203], v[200:201]
	v_rcp_f32_e32 v202, v199
	v_and_b32_e32 v199, 0xffff0000, v216
	v_max_f32_e32 v199, 0x1e3ce508, v199
	v_rcp_f32_e32 v203, v199
	v_lshlrev_b32_e32 v199, 16, v217
	v_pk_mul_f32 v[118:119], v[118:119], v[200:201]
	v_lshlrev_b32_e32 v200, 16, v208
	v_and_b32_e32 v201, 0xffff0000, v208
	v_max_f32_e32 v199, 0x1e3ce508, v199
	v_pk_mul_f32 v[200:201], v[202:203], v[200:201]
	v_rcp_f32_e32 v202, v199
	v_and_b32_e32 v199, 0xffff0000, v217
	v_max_f32_e32 v199, 0x1e3ce508, v199
	v_rcp_f32_e32 v203, v199
	v_lshlrev_b32_e32 v199, 16, v222
	v_pk_mul_f32 v[112:113], v[112:113], v[200:201]
	v_lshlrev_b32_e32 v200, 16, v209
	v_and_b32_e32 v201, 0xffff0000, v209
	v_max_f32_e32 v199, 0x1e3ce508, v199
	v_pk_mul_f32 v[200:201], v[202:203], v[200:201]
	v_rcp_f32_e32 v202, v199
	v_and_b32_e32 v199, 0xffff0000, v222
	v_max_f32_e32 v199, 0x1e3ce508, v199
	v_rcp_f32_e32 v203, v199
	v_lshlrev_b32_e32 v199, 16, v223
	v_pk_mul_f32 v[114:115], v[114:115], v[200:201]
	v_lshlrev_b32_e32 v200, 16, v218
	v_and_b32_e32 v201, 0xffff0000, v218
	v_max_f32_e32 v199, 0x1e3ce508, v199
	v_pk_mul_f32 v[200:201], v[202:203], v[200:201]
	v_rcp_f32_e32 v202, v199
	v_and_b32_e32 v199, 0xffff0000, v223
	v_max_f32_e32 v199, 0x1e3ce508, v199
	v_rcp_f32_e32 v203, v199
	v_lshlrev_b32_e32 v199, 16, v224
	v_pk_mul_f32 v[108:109], v[108:109], v[200:201]
	v_lshlrev_b32_e32 v200, 16, v219
	v_and_b32_e32 v201, 0xffff0000, v219
	v_max_f32_e32 v199, 0x1e3ce508, v199
	v_pk_mul_f32 v[200:201], v[202:203], v[200:201]
	v_rcp_f32_e32 v202, v199
	v_and_b32_e32 v199, 0xffff0000, v224
	v_max_f32_e32 v199, 0x1e3ce508, v199
	v_rcp_f32_e32 v203, v199
	v_lshlrev_b32_e32 v199, 16, v225
	v_pk_mul_f32 v[110:111], v[110:111], v[200:201]
	v_lshlrev_b32_e32 v200, 16, v220
	v_and_b32_e32 v201, 0xffff0000, v220
	v_max_f32_e32 v199, 0x1e3ce508, v199
	v_pk_mul_f32 v[200:201], v[202:203], v[200:201]
	v_rcp_f32_e32 v202, v199
	v_and_b32_e32 v199, 0xffff0000, v225
	v_max_f32_e32 v199, 0x1e3ce508, v199
	v_rcp_f32_e32 v203, v199
	v_pk_mul_f32 v[104:105], v[104:105], v[200:201]
	v_lshlrev_b32_e32 v200, 16, v221
	v_and_b32_e32 v201, 0xffff0000, v221
	v_pk_mul_f32 v[200:201], v[202:203], v[200:201]
	v_lshlrev_b32_e32 v199, 16, v164
	v_and_b32_e32 v164, 0xffff0000, v164
	v_pk_mul_f32 v[106:107], v[106:107], v[200:201]
	v_lshlrev_b32_e32 v200, 16, v160
	v_and_b32_e32 v201, 0xffff0000, v160
	v_lshlrev_b32_e32 v160, 16, v165
	v_max_f32_e32 v164, 0x1e3ce508, v164
	v_max_f32_e32 v160, 0x1e3ce508, v160
	v_rcp_f32_e32 v203, v164
	v_rcp_f32_e32 v164, v160
	v_and_b32_e32 v160, 0xffff0000, v165
	v_max_f32_e32 v160, 0x1e3ce508, v160
	v_rcp_f32_e32 v165, v160
	v_lshlrev_b32_e32 v160, 16, v161
	v_and_b32_e32 v161, 0xffff0000, v161
	v_max_f32_e32 v199, v199, v199
	v_pk_mul_f32 v[160:161], v[164:165], v[160:161]
	v_lshlrev_b32_e32 v164, 16, v166
	v_and_b32_e32 v165, 0xffff0000, v166
	v_max_f32_e32 v164, 0x1e3ce508, v164
	v_max_f32_e32 v165, 0x1e3ce508, v165
	v_rcp_f32_e32 v164, v164
	v_rcp_f32_e32 v165, v165
	v_pk_mul_f32 v[102:103], v[102:103], v[160:161]
	v_lshlrev_b32_e32 v160, 16, v162
	v_and_b32_e32 v161, 0xffff0000, v162
	v_lshlrev_b32_e32 v162, 16, v167
	v_max_f32_e32 v162, 0x1e3ce508, v162
	v_pk_mul_f32 v[160:161], v[164:165], v[160:161]
	v_rcp_f32_e32 v164, v162
	v_and_b32_e32 v162, 0xffff0000, v167
	v_max_f32_e32 v162, 0x1e3ce508, v162
	v_rcp_f32_e32 v165, v162
	v_pk_mul_f32 v[96:97], v[96:97], v[160:161]
	v_lshlrev_b32_e32 v160, 16, v163
	v_and_b32_e32 v161, 0xffff0000, v163
	v_pk_mul_f32 v[160:161], v[164:165], v[160:161]
	v_lshlrev_b32_e32 v162, 16, v156
	v_and_b32_e32 v156, 0xffff0000, v156
	v_pk_mul_f32 v[98:99], v[98:99], v[160:161]
	v_lshlrev_b32_e32 v160, 16, v152
	v_and_b32_e32 v161, 0xffff0000, v152
	v_lshlrev_b32_e32 v152, 16, v157
	v_max_f32_e32 v156, 0x1e3ce508, v156
	v_max_f32_e32 v152, 0x1e3ce508, v152
	v_rcp_f32_e32 v163, v156
	v_rcp_f32_e32 v156, v152
	v_and_b32_e32 v152, 0xffff0000, v157
	v_max_f32_e32 v152, 0x1e3ce508, v152
	v_rcp_f32_e32 v157, v152
	v_lshlrev_b32_e32 v152, 16, v153
	v_and_b32_e32 v153, 0xffff0000, v153
	v_max_f32_e32 v162, v162, v162
	v_pk_mul_f32 v[152:153], v[156:157], v[152:153]
	v_lshlrev_b32_e32 v156, 16, v158
	v_and_b32_e32 v157, 0xffff0000, v158
	v_max_f32_e32 v156, 0x1e3ce508, v156
	v_max_f32_e32 v157, 0x1e3ce508, v157
	v_rcp_f32_e32 v156, v156
	v_rcp_f32_e32 v157, v157
	v_pk_mul_f32 v[94:95], v[94:95], v[152:153]
	v_lshlrev_b32_e32 v152, 16, v154
	v_and_b32_e32 v153, 0xffff0000, v154
	v_lshlrev_b32_e32 v154, 16, v159
	v_max_f32_e32 v154, 0x1e3ce508, v154
	v_pk_mul_f32 v[152:153], v[156:157], v[152:153]
	v_rcp_f32_e32 v156, v154
	v_and_b32_e32 v154, 0xffff0000, v159
	v_max_f32_e32 v154, 0x1e3ce508, v154
	v_rcp_f32_e32 v157, v154
	v_pk_mul_f32 v[88:89], v[88:89], v[152:153]
	v_lshlrev_b32_e32 v152, 16, v155
	v_and_b32_e32 v153, 0xffff0000, v155
	v_pk_mul_f32 v[152:153], v[156:157], v[152:153]
	v_lshlrev_b32_e32 v154, 16, v148
	v_and_b32_e32 v148, 0xffff0000, v148
	v_pk_mul_f32 v[90:91], v[90:91], v[152:153]
	v_lshlrev_b32_e32 v152, 16, v144
	v_and_b32_e32 v153, 0xffff0000, v144
	v_lshlrev_b32_e32 v144, 16, v149
	v_max_f32_e32 v148, 0x1e3ce508, v148
	v_max_f32_e32 v144, 0x1e3ce508, v144
	v_rcp_f32_e32 v155, v148
	v_rcp_f32_e32 v148, v144
	v_and_b32_e32 v144, 0xffff0000, v149
	v_max_f32_e32 v144, 0x1e3ce508, v144
	v_rcp_f32_e32 v149, v144
	v_lshlrev_b32_e32 v144, 16, v145
	v_and_b32_e32 v145, 0xffff0000, v145
	v_max_f32_e32 v154, v154, v154
	v_pk_mul_f32 v[144:145], v[148:149], v[144:145]
	v_lshlrev_b32_e32 v148, 16, v150
	v_and_b32_e32 v149, 0xffff0000, v150
	v_max_f32_e32 v148, 0x1e3ce508, v148
	v_max_f32_e32 v149, 0x1e3ce508, v149
	v_rcp_f32_e32 v148, v148
	v_rcp_f32_e32 v149, v149
	v_pk_mul_f32 v[86:87], v[86:87], v[144:145]
	v_lshlrev_b32_e32 v144, 16, v146
	v_and_b32_e32 v145, 0xffff0000, v146
	v_lshlrev_b32_e32 v146, 16, v151
	v_max_f32_e32 v146, 0x1e3ce508, v146
	v_pk_mul_f32 v[144:145], v[148:149], v[144:145]
	v_rcp_f32_e32 v148, v146
	v_and_b32_e32 v146, 0xffff0000, v151
	v_max_f32_e32 v146, 0x1e3ce508, v146
	v_rcp_f32_e32 v149, v146
	v_pk_mul_f32 v[80:81], v[80:81], v[144:145]
	v_lshlrev_b32_e32 v144, 16, v147
	v_and_b32_e32 v145, 0xffff0000, v147
	v_pk_mul_f32 v[144:145], v[148:149], v[144:145]
	v_lshlrev_b32_e32 v146, 16, v140
	v_and_b32_e32 v140, 0xffff0000, v140
	v_pk_mul_f32 v[82:83], v[82:83], v[144:145]
	v_lshlrev_b32_e32 v144, 16, v136
	v_and_b32_e32 v145, 0xffff0000, v136
	v_lshlrev_b32_e32 v136, 16, v141
	v_max_f32_e32 v140, 0x1e3ce508, v140
	v_max_f32_e32 v136, 0x1e3ce508, v136
	v_rcp_f32_e32 v147, v140
	v_rcp_f32_e32 v140, v136
	v_and_b32_e32 v136, 0xffff0000, v141
	v_max_f32_e32 v136, 0x1e3ce508, v136
	v_rcp_f32_e32 v141, v136
	v_lshlrev_b32_e32 v136, 16, v137
	v_and_b32_e32 v137, 0xffff0000, v137
	v_max_f32_e32 v146, v146, v146
	v_pk_mul_f32 v[136:137], v[140:141], v[136:137]
	v_lshlrev_b32_e32 v140, 16, v142
	v_and_b32_e32 v141, 0xffff0000, v142
	v_max_f32_e32 v140, 0x1e3ce508, v140
	v_max_f32_e32 v141, 0x1e3ce508, v141
	v_rcp_f32_e32 v140, v140
	v_rcp_f32_e32 v141, v141
	v_pk_mul_f32 v[78:79], v[78:79], v[136:137]
	v_lshlrev_b32_e32 v136, 16, v138
	v_and_b32_e32 v137, 0xffff0000, v138
	v_lshlrev_b32_e32 v138, 16, v143
	v_max_f32_e32 v138, 0x1e3ce508, v138
	v_pk_mul_f32 v[136:137], v[140:141], v[136:137]
	v_rcp_f32_e32 v140, v138
	v_and_b32_e32 v138, 0xffff0000, v143
	v_max_f32_e32 v138, 0x1e3ce508, v138
	v_rcp_f32_e32 v141, v138
	v_pk_mul_f32 v[72:73], v[72:73], v[136:137]
	v_lshlrev_b32_e32 v136, 16, v139
	v_and_b32_e32 v137, 0xffff0000, v139
	v_pk_mul_f32 v[136:137], v[140:141], v[136:137]
	v_lshlrev_b32_e32 v138, 16, v132
	v_and_b32_e32 v132, 0xffff0000, v132
	v_pk_mul_f32 v[74:75], v[74:75], v[136:137]
	v_lshlrev_b32_e32 v136, 16, v128
	v_and_b32_e32 v137, 0xffff0000, v128
	v_lshlrev_b32_e32 v128, 16, v133
	v_max_f32_e32 v132, 0x1e3ce508, v132
	v_max_f32_e32 v128, 0x1e3ce508, v128
	v_rcp_f32_e32 v139, v132
	v_rcp_f32_e32 v132, v128
	v_and_b32_e32 v128, 0xffff0000, v133
	v_max_f32_e32 v128, 0x1e3ce508, v128
	v_rcp_f32_e32 v133, v128
	v_lshlrev_b32_e32 v128, 16, v129
	v_and_b32_e32 v129, 0xffff0000, v129
	v_pk_mul_f32 v[128:129], v[132:133], v[128:129]
	v_lshlrev_b32_e32 v132, 16, v134
	v_and_b32_e32 v133, 0xffff0000, v134
	v_max_f32_e32 v132, 0x1e3ce508, v132
	v_max_f32_e32 v133, 0x1e3ce508, v133
	v_rcp_f32_e32 v132, v132
	v_rcp_f32_e32 v133, v133
	v_pk_mul_f32 v[70:71], v[70:71], v[128:129]
	v_lshlrev_b32_e32 v128, 16, v130
	v_and_b32_e32 v129, 0xffff0000, v130
	v_lshlrev_b32_e32 v130, 16, v135
	v_max_f32_e32 v130, 0x1e3ce508, v130
	v_pk_mul_f32 v[128:129], v[132:133], v[128:129]
	v_rcp_f32_e32 v132, v130
	v_and_b32_e32 v130, 0xffff0000, v135
	v_max_f32_e32 v199, 0x1e3ce508, v199
	v_max_f32_e32 v162, 0x1e3ce508, v162
	v_max_f32_e32 v154, 0x1e3ce508, v154
	v_max_f32_e32 v146, 0x1e3ce508, v146
	v_max_f32_e32 v138, 0x1e3ce508, v138
	v_max_f32_e32 v130, 0x1e3ce508, v130
	v_rcp_f32_e32 v202, v199
	v_rcp_f32_e32 v162, v162
	v_rcp_f32_e32 v154, v154
	v_rcp_f32_e32 v146, v146
	v_rcp_f32_e32 v138, v138
	v_rcp_f32_e32 v133, v130
	v_pk_mul_f32 v[64:65], v[64:65], v[128:129]
	v_lshlrev_b32_e32 v128, 16, v131
	v_and_b32_e32 v129, 0xffff0000, v131
	v_pk_mul_f32 v[226:227], v[226:227], v[228:229]
	v_pk_mul_f32 v[200:201], v[202:203], v[200:201]
	v_pk_mul_f32 v[160:161], v[162:163], v[160:161]
	v_pk_mul_f32 v[152:153], v[154:155], v[152:153]
	v_pk_mul_f32 v[144:145], v[146:147], v[144:145]
	v_pk_mul_f32 v[136:137], v[138:139], v[136:137]
	v_pk_mul_f32 v[128:129], v[132:133], v[128:129]
	v_pk_mul_f32 v[124:125], v[124:125], v[226:227]
	v_pk_mul_f32 v[100:101], v[100:101], v[200:201]
	v_pk_mul_f32 v[92:93], v[92:93], v[160:161]
	v_pk_mul_f32 v[84:85], v[84:85], v[152:153]
	v_pk_mul_f32 v[76:77], v[76:77], v[144:145]
	v_pk_mul_f32 v[68:69], v[68:69], v[136:137]
	v_pk_mul_f32 v[66:67], v[66:67], v[128:129]
	v_add_u32_e32 v128, 0x80, v198
	v_mad_i64_i32 v[128:129], s[30:31], v128, s49, v[188:189]
	v_lshl_add_u64 v[128:129], v[128:129], 0, s[28:29]
	v_lshl_add_u64 v[128:129], v[128:129], 0, v[190:191]
	v_lshl_add_u64 v[130:131], v[128:129], 0, s[18:19]
	global_load_dwordx4 v[200:203], v[128:129], off offset:3584
	global_load_dwordx4 v[206:209], v[128:129], off offset:3840
	global_load_dwordx4 v[210:213], v[130:131], off offset:2048
	global_load_dwordx4 v[214:217], v[130:131], off offset:2304
	v_add_u32_e32 v128, 0x90, v198
	v_mad_i64_i32 v[128:129], s[30:31], v128, s49, v[188:189]
	v_lshl_add_u64 v[128:129], v[128:129], 0, s[28:29]
	v_lshl_add_u64 v[128:129], v[128:129], 0, v[190:191]
	v_lshl_add_u64 v[130:131], v[128:129], 0, s[18:19]
	global_load_dwordx4 v[218:221], v[128:129], off offset:3584
	global_load_dwordx4 v[160:163], v[128:129], off offset:3840
	global_load_dwordx4 v[222:225], v[130:131], off offset:2048
	global_load_dwordx4 v[164:167], v[130:131], off offset:2304
	v_add_u32_e32 v128, 0xa0, v198
	v_mad_i64_i32 v[128:129], s[30:31], v128, s49, v[188:189]
	v_lshl_add_u64 v[128:129], v[128:129], 0, s[28:29]
	v_lshl_add_u64 v[128:129], v[128:129], 0, v[190:191]
	v_lshl_add_u64 v[130:131], v[128:129], 0, s[18:19]
	global_load_dwordx4 v[152:155], v[128:129], off offset:3584
	global_load_dwordx4 v[144:147], v[128:129], off offset:3840
	global_load_dwordx4 v[156:159], v[130:131], off offset:2048
	global_load_dwordx4 v[148:151], v[130:131], off offset:2304
	v_add_u32_e32 v128, 0xb0, v198
	v_mad_i64_i32 v[128:129], s[30:31], v128, s49, v[188:189]
	v_lshl_add_u64 v[128:129], v[128:129], 0, s[28:29]
	v_lshl_add_u64 v[128:129], v[128:129], 0, v[190:191]
	v_lshl_add_u64 v[132:133], v[128:129], 0, s[18:19]
	global_load_dwordx4 v[136:139], v[128:129], off offset:3584
	s_nop 0
	global_load_dwordx4 v[128:131], v[128:129], off offset:3840
	s_nop 0
	global_load_dwordx4 v[140:143], v[132:133], off offset:2048
	s_nop 0
	global_load_dwordx4 v[132:135], v[132:133], off offset:2304
	s_waitcnt vmcnt(13)
	v_lshlrev_b32_e32 v188, 16, v210
	v_and_b32_e32 v189, 0xffff0000, v210
	v_max_f32_e32 v188, 0x1e3ce508, v188
	v_max_f32_e32 v189, 0x1e3ce508, v189
	v_rcp_f32_e32 v188, v188
	v_rcp_f32_e32 v189, v189
	v_lshlrev_b32_e32 v190, 16, v200
	v_and_b32_e32 v191, 0xffff0000, v200
	v_pk_mul_f32 v[188:189], v[188:189], v[190:191]
	v_lshlrev_b32_e32 v190, 16, v211
	v_and_b32_e32 v191, 0xffff0000, v211
	v_max_f32_e32 v190, 0x1e3ce508, v190
	v_max_f32_e32 v191, 0x1e3ce508, v191
	v_rcp_f32_e32 v190, v190
	v_rcp_f32_e32 v191, v191
	v_pk_mul_f32 v[60:61], v[60:61], v[188:189]
	v_lshlrev_b32_e32 v188, 16, v201
	v_and_b32_e32 v189, 0xffff0000, v201
	v_pk_mul_f32 v[188:189], v[190:191], v[188:189]
	v_lshlrev_b32_e32 v190, 16, v212
	v_and_b32_e32 v191, 0xffff0000, v212
	v_max_f32_e32 v190, 0x1e3ce508, v190
	v_max_f32_e32 v191, 0x1e3ce508, v191
	v_rcp_f32_e32 v190, v190
	v_rcp_f32_e32 v191, v191
	v_pk_mul_f32 v[62:63], v[62:63], v[188:189]
	v_lshlrev_b32_e32 v188, 16, v202
	v_and_b32_e32 v189, 0xffff0000, v202
	v_pk_mul_f32 v[188:189], v[190:191], v[188:189]
	v_lshlrev_b32_e32 v190, 16, v213
	v_and_b32_e32 v191, 0xffff0000, v213
	v_max_f32_e32 v190, 0x1e3ce508, v190
	v_max_f32_e32 v191, 0x1e3ce508, v191
	v_rcp_f32_e32 v190, v190
	v_rcp_f32_e32 v191, v191
	v_pk_mul_f32 v[56:57], v[56:57], v[188:189]
	v_lshlrev_b32_e32 v188, 16, v203
	v_and_b32_e32 v189, 0xffff0000, v203
	v_pk_mul_f32 v[188:189], v[190:191], v[188:189]
	s_waitcnt vmcnt(12)
	v_lshlrev_b32_e32 v190, 16, v214
	v_and_b32_e32 v191, 0xffff0000, v214
	v_max_f32_e32 v190, 0x1e3ce508, v190
	v_max_f32_e32 v191, 0x1e3ce508, v191
	v_rcp_f32_e32 v190, v190
	v_rcp_f32_e32 v191, v191
	v_pk_mul_f32 v[58:59], v[58:59], v[188:189]
	v_lshlrev_b32_e32 v188, 16, v206
	v_and_b32_e32 v189, 0xffff0000, v206
	v_pk_mul_f32 v[188:189], v[190:191], v[188:189]
	v_lshlrev_b32_e32 v190, 16, v215
	v_and_b32_e32 v191, 0xffff0000, v215
	v_max_f32_e32 v190, 0x1e3ce508, v190
	v_max_f32_e32 v191, 0x1e3ce508, v191
	v_rcp_f32_e32 v190, v190
	v_rcp_f32_e32 v191, v191
	v_pk_mul_f32 v[52:53], v[52:53], v[188:189]
	v_lshlrev_b32_e32 v188, 16, v207
	v_and_b32_e32 v189, 0xffff0000, v207
	v_pk_mul_f32 v[188:189], v[190:191], v[188:189]
	v_lshlrev_b32_e32 v190, 16, v216
	v_and_b32_e32 v191, 0xffff0000, v216
	v_max_f32_e32 v190, 0x1e3ce508, v190
	v_max_f32_e32 v191, 0x1e3ce508, v191
	v_rcp_f32_e32 v190, v190
	v_rcp_f32_e32 v191, v191
	v_pk_mul_f32 v[54:55], v[54:55], v[188:189]
	v_lshlrev_b32_e32 v188, 16, v208
	v_and_b32_e32 v189, 0xffff0000, v208
	v_pk_mul_f32 v[188:189], v[190:191], v[188:189]
	v_lshlrev_b32_e32 v190, 16, v217
	v_and_b32_e32 v191, 0xffff0000, v217
	v_max_f32_e32 v190, 0x1e3ce508, v190
	v_max_f32_e32 v191, 0x1e3ce508, v191
	v_rcp_f32_e32 v190, v190
	v_rcp_f32_e32 v191, v191
	v_pk_mul_f32 v[48:49], v[48:49], v[188:189]
	v_lshlrev_b32_e32 v188, 16, v209
	v_and_b32_e32 v189, 0xffff0000, v209
	v_pk_mul_f32 v[188:189], v[190:191], v[188:189]
	s_waitcnt vmcnt(9)
	v_lshlrev_b32_e32 v190, 16, v222
	v_and_b32_e32 v191, 0xffff0000, v222
	v_max_f32_e32 v190, 0x1e3ce508, v190
	v_max_f32_e32 v191, 0x1e3ce508, v191
	v_rcp_f32_e32 v190, v190
	v_rcp_f32_e32 v191, v191
	v_pk_mul_f32 v[50:51], v[50:51], v[188:189]
	v_lshlrev_b32_e32 v188, 16, v218
	v_and_b32_e32 v189, 0xffff0000, v218
	v_pk_mul_f32 v[188:189], v[190:191], v[188:189]
	v_lshlrev_b32_e32 v190, 16, v223
	v_and_b32_e32 v191, 0xffff0000, v223
	v_max_f32_e32 v190, 0x1e3ce508, v190
	v_max_f32_e32 v191, 0x1e3ce508, v191
	v_rcp_f32_e32 v190, v190
	v_rcp_f32_e32 v191, v191
	v_pk_mul_f32 v[44:45], v[44:45], v[188:189]
	v_lshlrev_b32_e32 v188, 16, v219
	v_and_b32_e32 v189, 0xffff0000, v219
	v_pk_mul_f32 v[188:189], v[190:191], v[188:189]
	v_lshlrev_b32_e32 v190, 16, v224
	v_and_b32_e32 v191, 0xffff0000, v224
	v_max_f32_e32 v190, 0x1e3ce508, v190
	v_max_f32_e32 v191, 0x1e3ce508, v191
	v_rcp_f32_e32 v190, v190
	v_rcp_f32_e32 v191, v191
	v_pk_mul_f32 v[46:47], v[46:47], v[188:189]
	v_lshlrev_b32_e32 v188, 16, v220
	v_and_b32_e32 v189, 0xffff0000, v220
	v_pk_mul_f32 v[188:189], v[190:191], v[188:189]
	v_lshlrev_b32_e32 v190, 16, v225
	v_and_b32_e32 v191, 0xffff0000, v225
	v_max_f32_e32 v190, 0x1e3ce508, v190
	v_max_f32_e32 v191, 0x1e3ce508, v191
	v_rcp_f32_e32 v190, v190
	v_rcp_f32_e32 v191, v191
	v_pk_mul_f32 v[40:41], v[40:41], v[188:189]
	v_lshlrev_b32_e32 v188, 16, v221
	v_and_b32_e32 v189, 0xffff0000, v221
	v_pk_mul_f32 v[188:189], v[190:191], v[188:189]
	s_waitcnt vmcnt(8)
	v_lshlrev_b32_e32 v190, 16, v164
	v_and_b32_e32 v164, 0xffff0000, v164
	v_pk_mul_f32 v[42:43], v[42:43], v[188:189]
	v_lshlrev_b32_e32 v188, 16, v160
	v_and_b32_e32 v189, 0xffff0000, v160
	v_lshlrev_b32_e32 v160, 16, v165
	v_max_f32_e32 v164, 0x1e3ce508, v164
	v_max_f32_e32 v160, 0x1e3ce508, v160
	v_rcp_f32_e32 v191, v164
	v_rcp_f32_e32 v164, v160
	v_and_b32_e32 v160, 0xffff0000, v165
	v_max_f32_e32 v160, 0x1e3ce508, v160
	v_rcp_f32_e32 v165, v160
	v_lshlrev_b32_e32 v160, 16, v161
	v_and_b32_e32 v161, 0xffff0000, v161
	v_max_f32_e32 v190, v190, v190
	v_pk_mul_f32 v[160:161], v[164:165], v[160:161]
	v_lshlrev_b32_e32 v164, 16, v166
	v_and_b32_e32 v165, 0xffff0000, v166
	v_max_f32_e32 v164, 0x1e3ce508, v164
	v_max_f32_e32 v165, 0x1e3ce508, v165
	v_rcp_f32_e32 v164, v164
	v_rcp_f32_e32 v165, v165
	v_pk_mul_f32 v[38:39], v[38:39], v[160:161]
	v_lshlrev_b32_e32 v160, 16, v162
	v_and_b32_e32 v161, 0xffff0000, v162
	v_lshlrev_b32_e32 v162, 16, v167
	v_max_f32_e32 v162, 0x1e3ce508, v162
	v_pk_mul_f32 v[160:161], v[164:165], v[160:161]
	v_rcp_f32_e32 v164, v162
	v_and_b32_e32 v162, 0xffff0000, v167
	v_max_f32_e32 v162, 0x1e3ce508, v162
	v_rcp_f32_e32 v165, v162
	v_pk_mul_f32 v[32:33], v[32:33], v[160:161]
	v_lshlrev_b32_e32 v160, 16, v163
	v_and_b32_e32 v161, 0xffff0000, v163
	v_pk_mul_f32 v[160:161], v[164:165], v[160:161]
	s_waitcnt vmcnt(5)
	v_lshlrev_b32_e32 v162, 16, v156
	v_and_b32_e32 v156, 0xffff0000, v156
	v_pk_mul_f32 v[34:35], v[34:35], v[160:161]
	v_lshlrev_b32_e32 v160, 16, v152
	v_and_b32_e32 v161, 0xffff0000, v152
	v_lshlrev_b32_e32 v152, 16, v157
	v_max_f32_e32 v156, 0x1e3ce508, v156
	v_max_f32_e32 v152, 0x1e3ce508, v152
	v_rcp_f32_e32 v163, v156
	v_rcp_f32_e32 v156, v152
	v_and_b32_e32 v152, 0xffff0000, v157
	v_max_f32_e32 v152, 0x1e3ce508, v152
	v_rcp_f32_e32 v157, v152
	v_lshlrev_b32_e32 v152, 16, v153
	v_and_b32_e32 v153, 0xffff0000, v153
	v_max_f32_e32 v162, v162, v162
	v_pk_mul_f32 v[152:153], v[156:157], v[152:153]
	v_lshlrev_b32_e32 v156, 16, v158
	v_and_b32_e32 v157, 0xffff0000, v158
	v_max_f32_e32 v156, 0x1e3ce508, v156
	v_max_f32_e32 v157, 0x1e3ce508, v157
	v_rcp_f32_e32 v156, v156
	v_rcp_f32_e32 v157, v157
	v_pk_mul_f32 v[30:31], v[30:31], v[152:153]
	v_lshlrev_b32_e32 v152, 16, v154
	v_and_b32_e32 v153, 0xffff0000, v154
	v_lshlrev_b32_e32 v154, 16, v159
	v_max_f32_e32 v154, 0x1e3ce508, v154
	v_pk_mul_f32 v[152:153], v[156:157], v[152:153]
	v_rcp_f32_e32 v156, v154
	v_and_b32_e32 v154, 0xffff0000, v159
	v_max_f32_e32 v154, 0x1e3ce508, v154
	v_rcp_f32_e32 v157, v154
	v_pk_mul_f32 v[24:25], v[24:25], v[152:153]
	v_lshlrev_b32_e32 v152, 16, v155
	v_and_b32_e32 v153, 0xffff0000, v155
	v_pk_mul_f32 v[152:153], v[156:157], v[152:153]
	s_waitcnt vmcnt(4)
	v_lshlrev_b32_e32 v154, 16, v148
	v_and_b32_e32 v148, 0xffff0000, v148
	v_pk_mul_f32 v[26:27], v[26:27], v[152:153]
	v_lshlrev_b32_e32 v152, 16, v144
	v_and_b32_e32 v153, 0xffff0000, v144
	v_lshlrev_b32_e32 v144, 16, v149
	v_max_f32_e32 v148, 0x1e3ce508, v148
	v_max_f32_e32 v144, 0x1e3ce508, v144
	v_rcp_f32_e32 v155, v148
	v_rcp_f32_e32 v148, v144
	v_and_b32_e32 v144, 0xffff0000, v149
	v_max_f32_e32 v144, 0x1e3ce508, v144
	v_rcp_f32_e32 v149, v144
	v_lshlrev_b32_e32 v144, 16, v145
	v_and_b32_e32 v145, 0xffff0000, v145
	v_max_f32_e32 v154, v154, v154
	v_pk_mul_f32 v[144:145], v[148:149], v[144:145]
	v_lshlrev_b32_e32 v148, 16, v150
	v_and_b32_e32 v149, 0xffff0000, v150
	v_max_f32_e32 v148, 0x1e3ce508, v148
	v_max_f32_e32 v149, 0x1e3ce508, v149
	v_rcp_f32_e32 v148, v148
	v_rcp_f32_e32 v149, v149
	v_pk_mul_f32 v[22:23], v[22:23], v[144:145]
	v_lshlrev_b32_e32 v144, 16, v146
	v_and_b32_e32 v145, 0xffff0000, v146
	v_lshlrev_b32_e32 v146, 16, v151
	v_max_f32_e32 v146, 0x1e3ce508, v146
	v_pk_mul_f32 v[144:145], v[148:149], v[144:145]
	v_rcp_f32_e32 v148, v146
	v_and_b32_e32 v146, 0xffff0000, v151
	v_max_f32_e32 v146, 0x1e3ce508, v146
	v_rcp_f32_e32 v149, v146
	v_pk_mul_f32 v[16:17], v[16:17], v[144:145]
	v_lshlrev_b32_e32 v144, 16, v147
	v_and_b32_e32 v145, 0xffff0000, v147
	v_pk_mul_f32 v[144:145], v[148:149], v[144:145]
	s_waitcnt vmcnt(1)
	v_lshlrev_b32_e32 v146, 16, v140
	v_and_b32_e32 v140, 0xffff0000, v140
	v_pk_mul_f32 v[18:19], v[18:19], v[144:145]
	v_lshlrev_b32_e32 v144, 16, v136
	v_and_b32_e32 v145, 0xffff0000, v136
	v_lshlrev_b32_e32 v136, 16, v141
	v_max_f32_e32 v140, 0x1e3ce508, v140
	v_max_f32_e32 v136, 0x1e3ce508, v136
	v_rcp_f32_e32 v147, v140
	v_rcp_f32_e32 v140, v136
	v_and_b32_e32 v136, 0xffff0000, v141
	v_max_f32_e32 v136, 0x1e3ce508, v136
	v_rcp_f32_e32 v141, v136
	v_lshlrev_b32_e32 v136, 16, v137
	v_and_b32_e32 v137, 0xffff0000, v137
	v_max_f32_e32 v146, v146, v146
	v_pk_mul_f32 v[136:137], v[140:141], v[136:137]
	v_lshlrev_b32_e32 v140, 16, v142
	v_and_b32_e32 v141, 0xffff0000, v142
	v_max_f32_e32 v140, 0x1e3ce508, v140
	v_max_f32_e32 v141, 0x1e3ce508, v141
	v_rcp_f32_e32 v140, v140
	v_rcp_f32_e32 v141, v141
	v_pk_mul_f32 v[14:15], v[14:15], v[136:137]
	v_lshlrev_b32_e32 v136, 16, v138
	v_and_b32_e32 v137, 0xffff0000, v138
	v_lshlrev_b32_e32 v138, 16, v143
	v_max_f32_e32 v138, 0x1e3ce508, v138
	v_pk_mul_f32 v[136:137], v[140:141], v[136:137]
	v_rcp_f32_e32 v140, v138
	v_and_b32_e32 v138, 0xffff0000, v143
	v_max_f32_e32 v138, 0x1e3ce508, v138
	v_rcp_f32_e32 v141, v138
	v_pk_mul_f32 v[8:9], v[8:9], v[136:137]
	v_lshlrev_b32_e32 v136, 16, v139
	v_and_b32_e32 v137, 0xffff0000, v139
	v_pk_mul_f32 v[136:137], v[140:141], v[136:137]
	s_waitcnt vmcnt(0)
	v_lshlrev_b32_e32 v138, 16, v132
	v_and_b32_e32 v132, 0xffff0000, v132
	v_pk_mul_f32 v[10:11], v[10:11], v[136:137]
	v_lshlrev_b32_e32 v136, 16, v128
	v_and_b32_e32 v137, 0xffff0000, v128
	v_lshlrev_b32_e32 v128, 16, v133
	v_max_f32_e32 v132, 0x1e3ce508, v132
	v_max_f32_e32 v128, 0x1e3ce508, v128
	v_rcp_f32_e32 v139, v132
	v_rcp_f32_e32 v132, v128
	v_and_b32_e32 v128, 0xffff0000, v133
	v_max_f32_e32 v128, 0x1e3ce508, v128
	v_rcp_f32_e32 v133, v128
	v_lshlrev_b32_e32 v128, 16, v129
	v_and_b32_e32 v129, 0xffff0000, v129
	v_pk_mul_f32 v[128:129], v[132:133], v[128:129]
	v_lshlrev_b32_e32 v132, 16, v134
	v_and_b32_e32 v133, 0xffff0000, v134
	v_max_f32_e32 v132, 0x1e3ce508, v132
	v_max_f32_e32 v133, 0x1e3ce508, v133
	v_rcp_f32_e32 v132, v132
	v_rcp_f32_e32 v133, v133
	v_pk_mul_f32 v[6:7], v[6:7], v[128:129]
	v_lshlrev_b32_e32 v128, 16, v130
	v_and_b32_e32 v129, 0xffff0000, v130
	v_lshlrev_b32_e32 v130, 16, v135
	v_max_f32_e32 v130, 0x1e3ce508, v130
	v_pk_mul_f32 v[128:129], v[132:133], v[128:129]
	v_rcp_f32_e32 v132, v130
	v_and_b32_e32 v130, 0xffff0000, v135
	v_max_f32_e32 v190, 0x1e3ce508, v190
	v_max_f32_e32 v162, 0x1e3ce508, v162
	v_max_f32_e32 v154, 0x1e3ce508, v154
	v_max_f32_e32 v146, 0x1e3ce508, v146
	v_max_f32_e32 v138, 0x1e3ce508, v138
	v_max_f32_e32 v130, 0x1e3ce508, v130
	v_rcp_f32_e32 v190, v190
	v_rcp_f32_e32 v162, v162
	v_rcp_f32_e32 v154, v154
	v_rcp_f32_e32 v146, v146
	v_rcp_f32_e32 v138, v138
	v_rcp_f32_e32 v133, v130
	v_pk_mul_f32 v[0:1], v[0:1], v[128:129]
	v_lshlrev_b32_e32 v128, 16, v131
	v_and_b32_e32 v129, 0xffff0000, v131
	v_pk_mul_f32 v[188:189], v[190:191], v[188:189]
	v_pk_mul_f32 v[160:161], v[162:163], v[160:161]
	v_pk_mul_f32 v[152:153], v[154:155], v[152:153]
	v_pk_mul_f32 v[144:145], v[146:147], v[144:145]
	v_pk_mul_f32 v[136:137], v[138:139], v[136:137]
	v_pk_mul_f32 v[128:129], v[132:133], v[128:129]
	v_pk_mul_f32 v[36:37], v[36:37], v[188:189]
	v_pk_mul_f32 v[28:29], v[28:29], v[160:161]
	v_pk_mul_f32 v[20:21], v[20:21], v[152:153]
	v_pk_mul_f32 v[12:13], v[12:13], v[144:145]
	v_pk_mul_f32 v[4:5], v[4:5], v[136:137]
	v_pk_mul_f32 v[2:3], v[2:3], v[128:129]
	s_branch .LBB0_2155
